# HGRN input-GEMM epilogue: 320 ds_bpermute cumsum shuffles replaced by DPP row_shr adds / row_newbcast (bit-identical), on top of K-tile LDS-DMA attention
# speedup vs baseline: 1.0145x; 1.0145x over previous
.LBB0_1946:
	s_lshl_b32 s86, s84, 7
	v_or_b32_e32 v128, s86, v154
	v_ashrrev_i32_e32 v129, 31, v128
	v_lshl_add_u64 v[132:133], v[128:129], 2, s[40:41]
	s_mov_b64 s[14:15], 0x1000
	global_load_dwordx4 v[128:131], v[132:133], off offset:16
	global_load_dwordx4 v[136:139], v[132:133], off
	v_lshl_add_u64 v[134:135], v[132:133], 0, s[14:15]
	v_add_co_u32_e32 v132, vcc, 0x1000, v132
	s_lshl_b64 s[14:15], s[88:89], 2
	s_nop 0
	v_addc_co_u32_e32 v133, vcc, 0, v133, vcc
	global_load_dwordx4 v[140:143], v[132:133], off
	s_nop 0
	global_load_dwordx4 v[132:135], v[134:135], off offset:16
	v_readlane_b32 s28, v255, 17
	s_add_u32 s92, s14, s28
	v_readlane_b32 s14, v255, 24
	s_addc_u32 s93, s15, s14
	s_ashr_i32 s85, s84, 31
	s_lshl_b64 s[90:91], s[84:85], 7
	s_ashr_i32 s87, s86, 31
	s_lshl_b64 s[14:15], s[92:93], 10
	s_add_u32 s67, s14, s90
	s_addc_u32 s85, s15, s91
	s_lshl_b64 s[94:95], s[92:93], 12
	v_lshlrev_b32_e32 v237, 2, v154
	s_waitcnt vmcnt(0)
	v_sub_f32_e32 v136, v136, v140
	v_mul_f32_e32 v136, 0x3fb8aa3b, v136
	v_exp_f32_e32 v136, v136
	s_nop 0
	v_add_f32_e32 v136, 1.0, v136
	v_rcp_f32_e32 v140, v136
	v_sub_f32_e32 v136, v137, v141
	v_and_or_b32 v137, v222, 64, v155
	v_lshl_or_b32 v232, v137, 2, 60
	v_add_f32_e32 v137, 1.0, v231
	v_rcp_f32_e32 v176, v137
	v_add_f32_e32 v137, 1.0, v230
	v_mul_f32_e32 v136, 0x3fb8aa3b, v136
	v_rcp_f32_e32 v177, v137
	v_add_f32_e32 v137, 1.0, v229
	v_exp_f32_e32 v136, v136
	v_rcp_f32_e32 v184, v137
	v_add_f32_e32 v137, 1.0, v228
	v_rcp_f32_e32 v185, v137
	v_add_f32_e32 v137, 1.0, v227
	v_rcp_f32_e32 v182, v137
	v_add_f32_e32 v137, 1.0, v226
	v_rcp_f32_e32 v183, v137
	v_add_f32_e32 v137, 1.0, v225
	v_add_f32_e32 v136, 1.0, v136
	v_rcp_f32_e32 v180, v137
	v_add_f32_e32 v137, 1.0, v224
	v_rcp_f32_e32 v141, v136
	v_and_b32_e32 v136, 0x70, v222
	v_rcp_f32_e32 v181, v137
	v_add_u32_e32 v137, -1, v222
	v_cmp_lt_i32_e32 vcc, v137, v136
	v_pk_add_f32 v[174:175], v[140:141], 1.0 op_sel_hi:[1,0] neg_lo:[1,0] neg_hi:[1,0]
	s_nop 0
	v_cndmask_b32_e32 v137, v137, v222, vcc
	v_lshlrev_b32_e32 v235, 2, v137
	v_add_u32_e32 v137, -2, v222
	v_cmp_lt_i32_e32 vcc, v137, v136
	v_pk_fma_f32 v[176:177], v[176:177], v[174:175], v[140:141]
	v_pk_fma_f32 v[184:185], v[184:185], v[174:175], v[140:141]
	v_cndmask_b32_e32 v137, v137, v222, vcc
	v_lshlrev_b32_e32 v234, 2, v137
	v_add_u32_e32 v137, -4, v222
	v_cmp_lt_i32_e32 vcc, v137, v136
	v_pk_fma_f32 v[182:183], v[182:183], v[174:175], v[140:141]
	v_pk_fma_f32 v[180:181], v[180:181], v[174:175], v[140:141]
	v_cndmask_b32_e32 v137, v137, v222, vcc
	v_lshlrev_b32_e32 v233, 2, v137
	v_add_u32_e32 v137, -8, v222
	v_cmp_lt_i32_e32 vcc, v137, v136
	s_nop 1
	v_cndmask_b32_e32 v136, v137, v222, vcc
	v_cmp_gt_f32_e32 vcc, s47, v176
	v_lshlrev_b32_e32 v236, 2, v136
	v_mov_b32_e32 v137, s85
	v_cndmask_b32_e64 v152, 0, 32, vcc
	v_ldexp_f32 v152, v176, v152
	v_log_f32_e32 v152, v152
	v_or_b32_e32 v136, s67, v154
	v_lshlrev_b64 v[136:137], 7, v[136:137]
	v_lshl_add_u64 v[136:137], v[164:165], 0, v[136:137]
	v_mul_f32_e32 v178, 0x3f317217, v152
	v_fma_f32 v178, v152, s96, -v178
	v_fmac_f32_e32 v178, 0x3377d1cf, v152
	v_fmac_f32_e32 v178, 0x3f317217, v152
	v_cmp_lt_f32_e64 s[14:15], |v152|, s1
	s_nop 1
	v_cndmask_b32_e64 v152, v152, v178, s[14:15]
	v_cndmask_b32_e32 v178, 0, v223, vcc
	v_cmp_gt_f32_e32 vcc, s47, v177
	v_sub_f32_e32 v152, v152, v178
	s_nop 0
	v_cndmask_b32_e64 v178, 0, 32, vcc
	v_ldexp_f32 v178, v177, v178
	v_log_f32_e32 v178, v178
	v_pk_add_f32 v[176:177], v[176:177], 1.0 op_sel_hi:[1,0] neg_lo:[1,0] neg_hi:[1,0]
	v_mul_f32_e32 v179, 0x3f317217, v178
	v_fma_f32 v179, v178, s96, -v179
	v_fmac_f32_e32 v179, 0x3377d1cf, v178
	v_fmac_f32_e32 v179, 0x3f317217, v178
	v_cmp_lt_f32_e64 s[14:15], |v178|, s1
	s_nop 1
	v_cndmask_b32_e64 v178, v178, v179, s[14:15]
	v_cndmask_b32_e32 v179, 0, v223, vcc
	v_sub_f32_e32 v178, v178, v179
	v_cmp_gt_f32_e32 vcc, s47, v184
	s_waitcnt lgkmcnt(0)
	s_nop 1
	v_add_f32_dpp v152, v152, v152 row_shr:1 row_mask:0xf bank_mask:0xf
	s_waitcnt lgkmcnt(0)
	s_nop 1
	v_add_f32_dpp v178, v178, v178 row_shr:1 row_mask:0xf bank_mask:0xf
	s_waitcnt lgkmcnt(0)
	s_nop 1
	v_add_f32_dpp v152, v152, v152 row_shr:2 row_mask:0xf bank_mask:0xf
	s_waitcnt lgkmcnt(0)
	s_nop 1
	v_add_f32_dpp v178, v178, v178 row_shr:2 row_mask:0xf bank_mask:0xf
	s_waitcnt lgkmcnt(0)
	s_nop 1
	v_add_f32_dpp v152, v152, v152 row_shr:4 row_mask:0xf bank_mask:0xf
	s_waitcnt lgkmcnt(0)
	s_nop 1
	v_add_f32_dpp v178, v178, v178 row_shr:4 row_mask:0xf bank_mask:0xf
	s_waitcnt lgkmcnt(0)
	s_nop 1
	v_add_f32_dpp v152, v152, v152 row_shr:8 row_mask:0xf bank_mask:0xf
	v_add_f32_e32 v187, 0, v152
	s_waitcnt lgkmcnt(0)
	s_nop 1
	v_add_f32_dpp v178, v178, v178 row_shr:8 row_mask:0xf bank_mask:0xf
	s_nop 1
	v_mov_b32_dpp v179, v152 row_newbcast:15 row_mask:0xf bank_mask:0xf
	v_add_f32_e32 v188, 0, v178
	s_waitcnt lgkmcnt(0)
	v_add_f32_e32 v152, 0, v179
	s_nop 1
	v_mov_b32_dpp v179, v178 row_newbcast:15 row_mask:0xf bank_mask:0xf
	v_mul_f32_e32 v178, 0xbfb8aa3b, v187
	v_cndmask_b32_e64 v187, 0, 32, vcc
	v_ldexp_f32 v187, v184, v187
	v_log_f32_e32 v187, v187
	s_waitcnt lgkmcnt(0)
	v_add_f32_e32 v186, 0, v179
	v_mul_f32_e32 v179, 0xbfb8aa3b, v188
	v_exp_f32_e32 v178, v178
	v_mul_f32_e32 v188, 0x3f317217, v187
	v_fma_f32 v188, v187, s96, -v188
	v_fmac_f32_e32 v188, 0x3377d1cf, v187
	v_fmac_f32_e32 v188, 0x3f317217, v187
	v_cmp_lt_f32_e64 s[14:15], |v187|, s1
	v_exp_f32_e32 v179, v179
	s_nop 0
	v_cndmask_b32_e64 v187, v187, v188, s[14:15]
	v_cndmask_b32_e32 v188, 0, v223, vcc
	v_cmp_gt_f32_e32 vcc, s47, v185
	v_sub_f32_e32 v187, v187, v188
	v_pk_mul_f32 v[176:177], v[176:177], v[178:179]
	v_cndmask_b32_e64 v188, 0, 32, vcc
	v_ldexp_f32 v188, v185, v188
	v_log_f32_e32 v188, v188
	v_pk_add_f32 v[184:185], v[184:185], 1.0 op_sel_hi:[1,0] neg_lo:[1,0] neg_hi:[1,0]
	v_mul_f32_e32 v189, 0x3f317217, v188
	v_fma_f32 v189, v188, s96, -v189
	v_fmac_f32_e32 v189, 0x3377d1cf, v188
	v_fmac_f32_e32 v189, 0x3f317217, v188
	v_cmp_lt_f32_e64 s[14:15], |v188|, s1
	s_nop 1
	v_cndmask_b32_e64 v188, v188, v189, s[14:15]
	v_cndmask_b32_e32 v189, 0, v223, vcc
	v_sub_f32_e32 v188, v188, v189
	v_cmp_gt_f32_e32 vcc, s47, v182
	s_waitcnt lgkmcnt(0)
	s_nop 1
	v_add_f32_dpp v187, v187, v187 row_shr:1 row_mask:0xf bank_mask:0xf
	s_waitcnt lgkmcnt(0)
	s_nop 1
	v_add_f32_dpp v188, v188, v188 row_shr:1 row_mask:0xf bank_mask:0xf
	s_waitcnt lgkmcnt(0)
	s_nop 1
	v_add_f32_dpp v187, v187, v187 row_shr:2 row_mask:0xf bank_mask:0xf
	s_waitcnt lgkmcnt(0)
	s_nop 1
	v_add_f32_dpp v188, v188, v188 row_shr:2 row_mask:0xf bank_mask:0xf
	s_waitcnt lgkmcnt(0)
	s_nop 1
	v_add_f32_dpp v187, v187, v187 row_shr:4 row_mask:0xf bank_mask:0xf
	s_waitcnt lgkmcnt(0)
	s_nop 1
	v_add_f32_dpp v188, v188, v188 row_shr:4 row_mask:0xf bank_mask:0xf
	s_waitcnt lgkmcnt(0)
	s_nop 1
	v_add_f32_dpp v187, v187, v187 row_shr:8 row_mask:0xf bank_mask:0xf
	s_waitcnt lgkmcnt(0)
	s_nop 1
	v_add_f32_dpp v188, v188, v188 row_shr:8 row_mask:0xf bank_mask:0xf
	s_nop 1
	v_mov_b32_dpp v189, v187 row_newbcast:15 row_mask:0xf bank_mask:0xf
	s_nop 1
	v_mov_b32_dpp v190, v188 row_newbcast:15 row_mask:0xf bank_mask:0xf
	v_add_f32_e32 v187, v187, v152
	v_add_f32_e32 v188, v188, v186
	s_waitcnt lgkmcnt(1)
	v_add_f32_e32 v152, v152, v189
	s_waitcnt lgkmcnt(0)
	v_add_f32_e32 v189, v186, v190
	v_mul_f32_e32 v186, 0xbfb8aa3b, v187
	v_mul_f32_e32 v187, 0xbfb8aa3b, v188
	v_cndmask_b32_e64 v188, 0, 32, vcc
	v_ldexp_f32 v188, v182, v188
	v_log_f32_e32 v188, v188
	v_exp_f32_e32 v186, v186
	v_exp_f32_e32 v187, v187
	v_mul_f32_e32 v190, 0x3f317217, v188
	v_fma_f32 v190, v188, s96, -v190
	v_fmac_f32_e32 v190, 0x3377d1cf, v188
	v_fmac_f32_e32 v190, 0x3f317217, v188
	v_cmp_lt_f32_e64 s[14:15], |v188|, s1
	v_pk_mul_f32 v[184:185], v[184:185], v[186:187]
	s_nop 0
	v_cndmask_b32_e64 v188, v188, v190, s[14:15]
	v_cndmask_b32_e32 v190, 0, v223, vcc
	v_cmp_gt_f32_e32 vcc, s47, v183
	v_sub_f32_e32 v188, v188, v190
	s_nop 0
	v_cndmask_b32_e64 v190, 0, 32, vcc
	v_ldexp_f32 v190, v183, v190
	v_log_f32_e32 v190, v190
	v_pk_add_f32 v[182:183], v[182:183], 1.0 op_sel_hi:[1,0] neg_lo:[1,0] neg_hi:[1,0]
	v_mul_f32_e32 v191, 0x3f317217, v190
	v_fma_f32 v191, v190, s96, -v191
	v_fmac_f32_e32 v191, 0x3377d1cf, v190
	v_fmac_f32_e32 v191, 0x3f317217, v190
	v_cmp_lt_f32_e64 s[14:15], |v190|, s1
	s_nop 1
	v_cndmask_b32_e64 v190, v190, v191, s[14:15]
	v_cndmask_b32_e32 v191, 0, v223, vcc
	v_sub_f32_e32 v190, v190, v191
	v_cmp_gt_f32_e32 vcc, s47, v180
	s_waitcnt lgkmcnt(0)
	s_nop 1
	v_add_f32_dpp v188, v188, v188 row_shr:1 row_mask:0xf bank_mask:0xf
	s_waitcnt lgkmcnt(0)
	s_nop 1
	v_add_f32_dpp v190, v190, v190 row_shr:1 row_mask:0xf bank_mask:0xf
	s_waitcnt lgkmcnt(0)
	s_nop 1
	v_add_f32_dpp v188, v188, v188 row_shr:2 row_mask:0xf bank_mask:0xf
	s_waitcnt lgkmcnt(0)
	s_nop 1
	v_add_f32_dpp v190, v190, v190 row_shr:2 row_mask:0xf bank_mask:0xf
	s_waitcnt lgkmcnt(0)
	s_nop 1
	v_add_f32_dpp v188, v188, v188 row_shr:4 row_mask:0xf bank_mask:0xf
	s_waitcnt lgkmcnt(0)
	s_nop 1
	v_add_f32_dpp v190, v190, v190 row_shr:4 row_mask:0xf bank_mask:0xf
	s_waitcnt lgkmcnt(0)
	s_nop 1
	v_add_f32_dpp v188, v188, v188 row_shr:8 row_mask:0xf bank_mask:0xf
	s_waitcnt lgkmcnt(0)
	s_nop 1
	v_add_f32_dpp v190, v190, v190 row_shr:8 row_mask:0xf bank_mask:0xf
	s_nop 1
	v_mov_b32_dpp v191, v188 row_newbcast:15 row_mask:0xf bank_mask:0xf
	v_add_f32_e32 v188, v188, v152
	s_nop 1
	v_mov_b32_dpp v196, v190 row_newbcast:15 row_mask:0xf bank_mask:0xf
	v_add_f32_e32 v190, v190, v189
	v_mul_f32_e32 v188, 0xbfb8aa3b, v188
	v_exp_f32_e32 v198, v188
	v_mul_f32_e32 v188, 0xbfb8aa3b, v190
	v_exp_f32_e32 v199, v188
	v_cndmask_b32_e64 v188, 0, 32, vcc
	v_ldexp_f32 v188, v180, v188
	v_log_f32_e32 v188, v188
	s_waitcnt lgkmcnt(1)
	v_add_f32_e32 v152, v152, v191
	s_waitcnt lgkmcnt(0)
	v_add_f32_e32 v189, v189, v196
	v_pk_mul_f32 v[182:183], v[182:183], v[198:199]
	v_mul_f32_e32 v190, 0x3f317217, v188
	v_fma_f32 v190, v188, s96, -v190
	v_fmac_f32_e32 v190, 0x3377d1cf, v188
	v_fmac_f32_e32 v190, 0x3f317217, v188
	v_cmp_lt_f32_e64 s[14:15], |v188|, s1
	s_nop 1
	v_cndmask_b32_e64 v188, v188, v190, s[14:15]
	v_cndmask_b32_e32 v190, 0, v223, vcc
	v_cmp_gt_f32_e32 vcc, s47, v181
	v_sub_f32_e32 v188, v188, v190
	s_nop 0
	v_cndmask_b32_e64 v190, 0, 32, vcc
	v_ldexp_f32 v190, v181, v190
	v_log_f32_e32 v190, v190
	v_pk_add_f32 v[180:181], v[180:181], 1.0 op_sel_hi:[1,0] neg_lo:[1,0] neg_hi:[1,0]
	v_mul_f32_e32 v191, 0x3f317217, v190
	v_fma_f32 v191, v190, s96, -v191
	v_fmac_f32_e32 v191, 0x3377d1cf, v190
	v_fmac_f32_e32 v191, 0x3f317217, v190
	v_cmp_lt_f32_e64 s[14:15], |v190|, s1
	s_nop 1
	v_cndmask_b32_e64 v190, v190, v191, s[14:15]
	v_cndmask_b32_e32 v191, 0, v223, vcc
	v_sub_f32_e32 v190, v190, v191
	s_waitcnt lgkmcnt(0)
	s_nop 1
	v_add_f32_dpp v188, v188, v188 row_shr:1 row_mask:0xf bank_mask:0xf
	s_waitcnt lgkmcnt(0)
	s_nop 1
	v_add_f32_dpp v190, v190, v190 row_shr:1 row_mask:0xf bank_mask:0xf
	s_waitcnt lgkmcnt(0)
	s_nop 1
	v_add_f32_dpp v188, v188, v188 row_shr:2 row_mask:0xf bank_mask:0xf
	s_waitcnt lgkmcnt(0)
	s_nop 1
	v_add_f32_dpp v190, v190, v190 row_shr:2 row_mask:0xf bank_mask:0xf
	s_waitcnt lgkmcnt(0)
	s_nop 1
	v_add_f32_dpp v188, v188, v188 row_shr:4 row_mask:0xf bank_mask:0xf
	s_waitcnt lgkmcnt(0)
	s_nop 1
	v_add_f32_dpp v190, v190, v190 row_shr:4 row_mask:0xf bank_mask:0xf
	s_waitcnt lgkmcnt(0)
	s_nop 1
	v_add_f32_dpp v188, v188, v188 row_shr:8 row_mask:0xf bank_mask:0xf
	v_add_f32_e32 v197, v188, v152
	s_waitcnt lgkmcnt(0)
	s_nop 1
	v_add_f32_dpp v190, v190, v190 row_shr:8 row_mask:0xf bank_mask:0xf
	s_nop 1
	v_mov_b32_dpp v191, v188 row_newbcast:15 row_mask:0xf bank_mask:0xf
	s_nop 1
	v_mov_b32_dpp v196, v190 row_newbcast:15 row_mask:0xf bank_mask:0xf
	v_add_f32_e32 v190, v190, v189
	s_waitcnt lgkmcnt(1)
	v_add_f32_e32 v152, v152, v191
	v_mul_f32_e32 v152, 0x3fb8aa3b, v152
	s_waitcnt lgkmcnt(0)
	v_add_f32_e32 v189, v189, v196
	v_exp_f32_e32 v188, v152
	v_mul_f32_e32 v152, 0x3fb8aa3b, v189
	v_exp_f32_e32 v189, v152
	v_mul_f32_e32 v152, v176, v188
	v_cvt_pk_bf16_f32 v152, v152, s0
	global_store_short v[136:137], v152, off
	v_mul_f32_e32 v152, v177, v189
	v_cvt_pk_bf16_f32 v152, v152, s0
	global_store_short v[136:137], v152, off offset:128
	v_mul_f32_e32 v152, v184, v188
	v_cvt_pk_bf16_f32 v152, v152, s0
	global_store_short v[136:137], v152, off offset:32
	v_mul_f32_e32 v152, v185, v189
	v_cvt_pk_bf16_f32 v152, v152, s0
	global_store_short v[136:137], v152, off offset:160
	v_mul_f32_e32 v152, v182, v188
	v_cvt_pk_bf16_f32 v152, v152, s0
	global_store_short v[136:137], v152, off offset:64
	v_mul_f32_e32 v152, v183, v189
	v_cvt_pk_bf16_f32 v152, v152, s0
	global_store_short v[136:137], v152, off offset:192
	v_mul_f32_e32 v152, 0xbfb8aa3b, v197
	v_exp_f32_e32 v200, v152
	v_mul_f32_e32 v152, 0xbfb8aa3b, v190
	v_exp_f32_e32 v201, v152
	s_nop 0
	v_pk_mul_f32 v[180:181], v[180:181], v[200:201]
	s_nop 0
	v_mul_f32_e32 v152, v188, v180
	v_cvt_pk_bf16_f32 v152, v152, s0
	global_store_short v[136:137], v152, off offset:96
	v_mul_f32_e32 v152, v189, v181
	v_cvt_pk_bf16_f32 v152, v152, s0
	global_store_short v[136:137], v152, off offset:224
	s_and_saveexec_b64 s[14:15], s[4:5]
	s_cbranch_execz .LBB0_1948
	s_add_u32 vcc_lo, s33, s94
	s_addc_u32 vcc_hi, s0, s95
	s_lshl_b64 s[88:89], s[86:87], 2
	s_add_u32 s88, vcc_lo, s88
	s_addc_u32 s89, vcc_hi, s89
	global_store_dwordx2 v237, v[188:189], s[88:89]
.LBB0_1948:
	s_or_b64 exec, exec, s[14:15]
	v_sub_f32_e32 v137, v139, v143
	v_mul_f32_e32 v139, 0xbfb8aa3b, v124
	v_mul_f32_e32 v143, 0xbfb8aa3b, v125
	v_exp_f32_e32 v139, v139
	v_exp_f32_e32 v143, v143
	v_sub_f32_e32 v136, v138, v142
	v_rcp_f32_e32 v138, v178
	v_add_f32_e32 v139, 1.0, v139
	v_add_f32_e32 v143, 1.0, v143
	v_rcp_f32_e32 v142, v139
	v_rcp_f32_e32 v143, v143
	v_rcp_f32_e32 v139, v179
	v_cvt_pk_bf16_f32 v190, v184, v185
	v_mul_f32_e32 v136, 0x3fb8aa3b, v136
	v_pk_mul_f32 v[142:143], v[124:125], v[142:143]
	v_mul_f32_e32 v137, 0x3fb8aa3b, v137
	v_pk_mul_f32 v[138:139], v[142:143], v[138:139]
	v_mul_f32_e32 v143, 0xbfb8aa3b, v109
	v_cvt_pk_bf16_f32 v188, v138, v139
	v_mul_f32_e32 v139, 0xbfb8aa3b, v108
	v_exp_f32_e32 v139, v139
	v_exp_f32_e32 v143, v143
	v_cvt_pk_bf16_f32 v142, v176, v177
	v_rcp_f32_e32 v138, v186
	v_add_f32_e32 v139, 1.0, v139
	v_add_f32_e32 v143, 1.0, v143
	v_rcp_f32_e32 v176, v139
	v_rcp_f32_e32 v177, v143
	v_rcp_f32_e32 v139, v187
	v_mul_f32_e32 v143, 0xbfb8aa3b, v93
	v_exp_f32_e32 v143, v143
	v_pk_mul_f32 v[176:177], v[108:109], v[176:177]
	v_exp_f32_e32 v136, v136
	v_pk_mul_f32 v[138:139], v[176:177], v[138:139]
	v_add_f32_e32 v143, 1.0, v143
	v_cvt_pk_bf16_f32 v196, v138, v139
	v_mul_f32_e32 v139, 0xbfb8aa3b, v92
	v_exp_f32_e32 v139, v139
	v_rcp_f32_e32 v177, v143
	v_rcp_f32_e32 v138, v198
	v_mul_f32_e32 v143, 0xbfb8aa3b, v77
	v_add_f32_e32 v139, 1.0, v139
	v_rcp_f32_e32 v176, v139
	v_rcp_f32_e32 v139, v199
	v_exp_f32_e32 v143, v143
	v_cvt_pk_bf16_f32 v198, v180, v181
	v_pk_mul_f32 v[176:177], v[92:93], v[176:177]
	v_exp_f32_e32 v137, v137
	v_pk_mul_f32 v[138:139], v[176:177], v[138:139]
	v_add_f32_e32 v143, 1.0, v143
	v_cvt_pk_bf16_f32 v204, v138, v139
	v_mul_f32_e32 v139, 0xbfb8aa3b, v76
	v_exp_f32_e32 v139, v139
	v_rcp_f32_e32 v177, v143
	v_mul_f32_e32 v143, 0xbfb8aa3b, v118
	v_exp_f32_e32 v143, v143
	v_add_f32_e32 v139, 1.0, v139
	v_rcp_f32_e32 v176, v139
	v_rcp_f32_e32 v138, v200
	v_rcp_f32_e32 v139, v201
	v_add_f32_e32 v143, 1.0, v143
	v_pk_mul_f32 v[176:177], v[76:77], v[176:177]
	v_add_f32_e32 v136, 1.0, v136
	v_pk_mul_f32 v[138:139], v[176:177], v[138:139]
	v_rcp_f32_e32 v176, v143
	v_mul_f32_e32 v143, 0xbfb8aa3b, v119
	v_exp_f32_e32 v143, v143
	v_add_f32_e32 v137, 1.0, v137
	v_rcp_f32_e32 v136, v136
	v_rcp_f32_e32 v137, v137
	v_add_f32_e32 v143, 1.0, v143
	v_rcp_f32_e32 v177, v143
	v_mul_f32_e32 v143, 0xbfb8aa3b, v102
	v_exp_f32_e32 v143, v143
	v_cvt_pk_bf16_f32 v200, v138, v139
	v_pk_add_f32 v[138:139], v[136:137], 1.0 op_sel_hi:[1,0] neg_lo:[1,0] neg_hi:[1,0]
	v_mov_b32_e32 v179, s85
	v_add_f32_e32 v143, 1.0, v143
	v_rcp_f32_e32 v180, v143
	v_mul_f32_e32 v143, 0xbfb8aa3b, v103
	v_exp_f32_e32 v143, v143
	v_pk_fma_f32 v[176:177], v[176:177], v[138:139], v[136:137]
	v_or_b32_e32 v178, s67, v158
	v_cmp_gt_f32_e32 vcc, s47, v176
	v_add_f32_e32 v143, 1.0, v143
	v_rcp_f32_e32 v181, v143
	v_mul_f32_e32 v143, 0xbfb8aa3b, v86
	v_exp_f32_e32 v143, v143
	v_lshlrev_b64 v[178:179], 7, v[178:179]
	v_lshl_add_u64 v[206:207], v[164:165], 0, v[178:179]
	v_pk_fma_f32 v[180:181], v[180:181], v[138:139], v[136:137]
	v_add_f32_e32 v143, 1.0, v143
	v_rcp_f32_e32 v184, v143
	v_mul_f32_e32 v143, 0xbfb8aa3b, v87
	v_exp_f32_e32 v143, v143
	v_cvt_pk_bf16_f32 v202, v182, v183
	v_lshlrev_b64 v[208:209], 11, v[172:173]
	s_lshl_b64 s[88:89], s[86:87], 1
	v_add_f32_e32 v143, 1.0, v143
	v_rcp_f32_e32 v185, v143
	v_mul_f32_e32 v143, 0xbfb8aa3b, v70
	v_exp_f32_e32 v143, v143
	v_pk_fma_f32 v[184:185], v[184:185], v[138:139], v[136:137]
	v_add_f32_e32 v143, 1.0, v143
	v_rcp_f32_e32 v210, v143
	v_mul_f32_e32 v143, 0xbfb8aa3b, v71
	v_exp_f32_e32 v143, v143
	s_nop 0
	v_add_f32_e32 v143, 1.0, v143
	v_rcp_f32_e32 v211, v143
	v_cndmask_b32_e64 v143, 0, 32, vcc
	v_ldexp_f32 v143, v176, v143
	v_log_f32_e32 v143, v143
	v_pk_fma_f32 v[210:211], v[210:211], v[138:139], v[136:137]
	v_mul_f32_e32 v152, 0x3f317217, v143
	v_fma_f32 v152, v143, s96, -v152
	v_fmac_f32_e32 v152, 0x3377d1cf, v143
	v_fmac_f32_e32 v152, 0x3f317217, v143
	v_cmp_lt_f32_e64 s[14:15], |v143|, s1
	s_nop 1
	v_cndmask_b32_e64 v143, v143, v152, s[14:15]
	v_cndmask_b32_e32 v152, 0, v223, vcc
	v_cmp_gt_f32_e32 vcc, s47, v177
	v_sub_f32_e32 v143, v143, v152
	s_nop 0
	v_cndmask_b32_e64 v152, 0, 32, vcc
	v_ldexp_f32 v152, v177, v152
	v_log_f32_e32 v152, v152
	v_pk_add_f32 v[176:177], v[176:177], 1.0 op_sel_hi:[1,0] neg_lo:[1,0] neg_hi:[1,0]
	v_mul_f32_e32 v178, 0x3f317217, v152
	v_fma_f32 v178, v152, s96, -v178
	v_fmac_f32_e32 v178, 0x3377d1cf, v152
	v_fmac_f32_e32 v178, 0x3f317217, v152
	v_cmp_lt_f32_e64 s[14:15], |v152|, s1
	s_nop 1
	v_cndmask_b32_e64 v152, v152, v178, s[14:15]
	v_cndmask_b32_e32 v178, 0, v223, vcc
	v_cmp_gt_f32_e32 vcc, s47, v180
	v_sub_f32_e32 v152, v152, v178
	v_cndmask_b32_e64 v186, 0, 32, vcc
	v_ldexp_f32 v186, v180, v186
	v_log_f32_e32 v186, v186
	s_waitcnt lgkmcnt(0)
	s_nop 1
	v_add_f32_dpp v143, v143, v143 row_shr:1 row_mask:0xf bank_mask:0xf
	v_mul_f32_e32 v187, 0x3f317217, v186
	v_fma_f32 v187, v186, s96, -v187
	v_fmac_f32_e32 v187, 0x3377d1cf, v186
	v_fmac_f32_e32 v187, 0x3f317217, v186
	v_cmp_lt_f32_e64 s[14:15], |v186|, s1
	s_waitcnt lgkmcnt(0)
	v_cndmask_b32_e64 v186, v186, v187, s[14:15]
	v_cndmask_b32_e32 v187, 0, v223, vcc
	v_cmp_gt_f32_e32 vcc, s47, v181
	v_sub_f32_e32 v186, v186, v187
	s_nop 1
	v_add_f32_dpp v152, v152, v152 row_shr:1 row_mask:0xf bank_mask:0xf
	v_cndmask_b32_e64 v187, 0, 32, vcc
	v_ldexp_f32 v187, v181, v187
	v_log_f32_e32 v187, v187
	v_pk_add_f32 v[180:181], v[180:181], 1.0 op_sel_hi:[1,0] neg_lo:[1,0] neg_hi:[1,0]
	v_mul_f32_e32 v191, 0x3f317217, v187
	v_fma_f32 v191, v187, s96, -v191
	v_fmac_f32_e32 v191, 0x3377d1cf, v187
	v_fmac_f32_e32 v191, 0x3f317217, v187
	v_cmp_lt_f32_e64 s[14:15], |v187|, s1
	s_waitcnt lgkmcnt(0)
	s_nop 1
	v_add_f32_dpp v143, v143, v143 row_shr:2 row_mask:0xf bank_mask:0xf
	v_cndmask_b32_e64 v187, v187, v191, s[14:15]
	v_cndmask_b32_e32 v191, 0, v223, vcc
	v_sub_f32_e32 v187, v187, v191
	v_cmp_gt_f32_e32 vcc, s47, v184
	s_waitcnt lgkmcnt(1)
	s_nop 1
	v_add_f32_dpp v186, v186, v186 row_shr:1 row_mask:0xf bank_mask:0xf
	s_waitcnt lgkmcnt(1)
	s_nop 1
	v_add_f32_dpp v152, v152, v152 row_shr:2 row_mask:0xf bank_mask:0xf
	s_waitcnt lgkmcnt(1)
	s_nop 1
	v_add_f32_dpp v187, v187, v187 row_shr:1 row_mask:0xf bank_mask:0xf
	s_waitcnt lgkmcnt(1)
	s_nop 1
	v_add_f32_dpp v143, v143, v143 row_shr:4 row_mask:0xf bank_mask:0xf
	s_waitcnt lgkmcnt(1)
	s_nop 1
	v_add_f32_dpp v186, v186, v186 row_shr:2 row_mask:0xf bank_mask:0xf
	s_waitcnt lgkmcnt(1)
	s_nop 1
	v_add_f32_dpp v152, v152, v152 row_shr:4 row_mask:0xf bank_mask:0xf
	s_waitcnt lgkmcnt(1)
	s_nop 1
	v_add_f32_dpp v187, v187, v187 row_shr:2 row_mask:0xf bank_mask:0xf
	s_waitcnt lgkmcnt(1)
	s_nop 1
	v_add_f32_dpp v143, v143, v143 row_shr:8 row_mask:0xf bank_mask:0xf
	s_waitcnt lgkmcnt(1)
	s_nop 1
	v_add_f32_dpp v186, v186, v186 row_shr:4 row_mask:0xf bank_mask:0xf
	s_waitcnt lgkmcnt(1)
	s_nop 1
	v_add_f32_dpp v152, v152, v152 row_shr:8 row_mask:0xf bank_mask:0xf
	s_nop 1
	v_mov_b32_dpp v178, v143 row_newbcast:15 row_mask:0xf bank_mask:0xf
	v_add_f32_e32 v143, 0, v143
	s_waitcnt lgkmcnt(1)
	s_nop 1
	v_add_f32_dpp v187, v187, v187 row_shr:4 row_mask:0xf bank_mask:0xf
	s_waitcnt lgkmcnt(1)
	v_add_f32_e32 v182, 0, v178
	s_nop 1
	v_mov_b32_dpp v178, v152 row_newbcast:15 row_mask:0xf bank_mask:0xf
	v_add_f32_e32 v152, 0, v152
	v_mul_f32_e32 v143, 0xbfb8aa3b, v143
	s_waitcnt lgkmcnt(1)
	s_nop 1
	v_add_f32_dpp v186, v186, v186 row_shr:8 row_mask:0xf bank_mask:0xf
	s_waitcnt lgkmcnt(1)
	v_add_f32_e32 v183, 0, v178
	v_exp_f32_e32 v178, v143
	v_mul_f32_e32 v143, 0xbfb8aa3b, v152
	v_exp_f32_e32 v179, v143
	s_waitcnt lgkmcnt(0)
	s_nop 1
	v_add_f32_dpp v187, v187, v187 row_shr:8 row_mask:0xf bank_mask:0xf
	s_nop 1
	v_mov_b32_dpp v191, v186 row_newbcast:15 row_mask:0xf bank_mask:0xf
	v_add_f32_e32 v186, v186, v182
	s_nop 1
	v_mov_b32_dpp v197, v187 row_newbcast:15 row_mask:0xf bank_mask:0xf
	v_add_f32_e32 v187, v187, v183
	v_mul_f32_e32 v143, 0xbfb8aa3b, v126
	s_waitcnt lgkmcnt(1)
	v_add_f32_e32 v199, v182, v191
	v_mul_f32_e32 v182, 0xbfb8aa3b, v186
	v_cndmask_b32_e64 v186, 0, 32, vcc
	v_ldexp_f32 v186, v184, v186
	v_log_f32_e32 v186, v186
	s_waitcnt lgkmcnt(0)
	v_add_f32_e32 v201, v183, v197
	v_mul_f32_e32 v183, 0xbfb8aa3b, v187
	v_exp_f32_e32 v182, v182
	v_mul_f32_e32 v187, 0x3f317217, v186
	v_fma_f32 v187, v186, s96, -v187
	v_fmac_f32_e32 v187, 0x3377d1cf, v186
	v_fmac_f32_e32 v187, 0x3f317217, v186
	v_cmp_lt_f32_e64 s[14:15], |v186|, s1
	v_exp_f32_e32 v183, v183
	v_exp_f32_e32 v143, v143
	v_cndmask_b32_e64 v186, v186, v187, s[14:15]
	v_cndmask_b32_e32 v187, 0, v223, vcc
	v_cmp_gt_f32_e32 vcc, s47, v185
	v_sub_f32_e32 v186, v186, v187
	v_pk_mul_f32 v[214:215], v[180:181], v[182:183]
	v_cndmask_b32_e64 v187, 0, 32, vcc
	v_ldexp_f32 v187, v185, v187
	v_log_f32_e32 v187, v187
	v_mul_f32_e32 v181, 0xbfb8aa3b, v110
	v_add_f32_e32 v143, 1.0, v143
	v_exp_f32_e32 v181, v181
	v_mul_f32_e32 v203, 0x3f317217, v187
	v_fma_f32 v203, v187, s96, -v203
	v_fmac_f32_e32 v203, 0x3377d1cf, v187
	v_fmac_f32_e32 v203, 0x3f317217, v187
	v_cmp_lt_f32_e64 s[14:15], |v187|, s1
	v_pk_mul_f32 v[212:213], v[176:177], v[178:179]
	v_rcp_f32_e32 v176, v178
	v_cndmask_b32_e64 v187, v187, v203, s[14:15]
	v_cndmask_b32_e32 v203, 0, v223, vcc
	v_cmp_gt_f32_e32 vcc, s47, v210
	v_sub_f32_e32 v187, v187, v203
	v_cndmask_b32_e64 v218, 0, 32, vcc
	v_ldexp_f32 v218, v210, v218
	v_log_f32_e32 v218, v218
	v_rcp_f32_e32 v178, v143
	s_waitcnt lgkmcnt(0)
	s_nop 1
	v_add_f32_dpp v186, v186, v186 row_shr:1 row_mask:0xf bank_mask:0xf
	v_mul_f32_e32 v219, 0x3f317217, v218
	v_fma_f32 v219, v218, s96, -v219
	v_fmac_f32_e32 v219, 0x3377d1cf, v218
	v_fmac_f32_e32 v219, 0x3f317217, v218
	v_cmp_lt_f32_e64 s[14:15], |v218|, s1
	v_mul_f32_e32 v143, 0xbfb8aa3b, v127
	v_cndmask_b32_e64 v218, v218, v219, s[14:15]
	v_cndmask_b32_e32 v219, 0, v223, vcc
	v_cmp_gt_f32_e32 vcc, s47, v211
	v_sub_f32_e32 v218, v218, v219
	s_waitcnt lgkmcnt(0)
	v_cndmask_b32_e64 v219, 0, 32, vcc
	v_ldexp_f32 v219, v211, v219
	v_log_f32_e32 v219, v219
	s_nop 1
	v_add_f32_dpp v187, v187, v187 row_shr:1 row_mask:0xf bank_mask:0xf
	v_exp_f32_e32 v143, v143
	v_mul_f32_e32 v220, 0x3f317217, v219
	v_fma_f32 v220, v219, s96, -v220
	v_fmac_f32_e32 v220, 0x3377d1cf, v219
	v_fmac_f32_e32 v220, 0x3f317217, v219
	v_cmp_lt_f32_e64 s[14:15], |v219|, s1
	s_waitcnt lgkmcnt(0)
	s_nop 1
	v_add_f32_dpp v186, v186, v186 row_shr:2 row_mask:0xf bank_mask:0xf
	v_cndmask_b32_e64 v219, v219, v220, s[14:15]
	v_cndmask_b32_e32 v220, 0, v223, vcc
	v_sub_f32_e32 v219, v219, v220
	v_pk_add_f32 v[184:185], v[184:185], 1.0 op_sel_hi:[1,0] neg_lo:[1,0] neg_hi:[1,0]
	v_add_f32_e32 v181, 1.0, v181
	v_rcp_f32_e32 v180, v182
	s_waitcnt lgkmcnt(1)
	s_nop 1
	v_add_f32_dpp v218, v218, v218 row_shr:1 row_mask:0xf bank_mask:0xf
	s_waitcnt lgkmcnt(1)
	s_nop 1
	v_add_f32_dpp v187, v187, v187 row_shr:2 row_mask:0xf bank_mask:0xf
	v_rcp_f32_e32 v182, v181
	s_waitcnt lgkmcnt(1)
	s_nop 1
	v_add_f32_dpp v219, v219, v219 row_shr:1 row_mask:0xf bank_mask:0xf
	s_waitcnt lgkmcnt(1)
	s_nop 1
	v_add_f32_dpp v186, v186, v186 row_shr:4 row_mask:0xf bank_mask:0xf
	v_rcp_f32_e32 v181, v183
	s_waitcnt lgkmcnt(1)
	s_nop 1
	v_add_f32_dpp v218, v218, v218 row_shr:2 row_mask:0xf bank_mask:0xf
	s_waitcnt lgkmcnt(1)
	s_nop 1
	v_add_f32_dpp v187, v187, v187 row_shr:4 row_mask:0xf bank_mask:0xf
	v_mul_f32_e32 v183, 0xbfb8aa3b, v111
	s_waitcnt lgkmcnt(1)
	s_nop 1
	v_add_f32_dpp v219, v219, v219 row_shr:2 row_mask:0xf bank_mask:0xf
	s_waitcnt lgkmcnt(1)
	s_nop 1
	v_add_f32_dpp v186, v186, v186 row_shr:8 row_mask:0xf bank_mask:0xf
	v_add_f32_e32 v143, 1.0, v143
	s_waitcnt lgkmcnt(1)
	s_nop 1
	v_add_f32_dpp v218, v218, v218 row_shr:4 row_mask:0xf bank_mask:0xf
	s_waitcnt lgkmcnt(1)
	s_nop 1
	v_add_f32_dpp v187, v187, v187 row_shr:8 row_mask:0xf bank_mask:0xf
	s_nop 1
	v_mov_b32_dpp v203, v186 row_newbcast:15 row_mask:0xf bank_mask:0xf
	s_nop 1
	v_mov_b32_dpp v205, v187 row_newbcast:15 row_mask:0xf bank_mask:0xf
	s_waitcnt lgkmcnt(2)
	s_nop 1
	v_add_f32_dpp v219, v219, v219 row_shr:4 row_mask:0xf bank_mask:0xf
	v_add_f32_e32 v186, v186, v199
	v_add_f32_e32 v187, v187, v201
	v_mul_f32_e32 v186, 0xbfb8aa3b, v186
	v_mul_f32_e32 v187, 0xbfb8aa3b, v187
	s_waitcnt lgkmcnt(0)
	s_nop 1
	v_add_f32_dpp v218, v218, v218 row_shr:8 row_mask:0xf bank_mask:0xf
	v_exp_f32_e32 v186, v186
	v_exp_f32_e32 v187, v187
	v_add_f32_e32 v199, v199, v203
	v_add_f32_e32 v238, v218, v199
	s_waitcnt lgkmcnt(0)
	s_nop 1
	v_add_f32_dpp v219, v219, v219 row_shr:8 row_mask:0xf bank_mask:0xf
	s_nop 1
	v_mov_b32_dpp v220, v218 row_newbcast:15 row_mask:0xf bank_mask:0xf
	s_nop 1
	v_mov_b32_dpp v221, v219 row_newbcast:15 row_mask:0xf bank_mask:0xf
	v_pk_mul_f32 v[216:217], v[184:185], v[186:187]
	v_mul_f32_e32 v185, 0xbfb8aa3b, v94
	v_exp_f32_e32 v185, v185
	s_waitcnt lgkmcnt(1)
	v_add_f32_e32 v199, v199, v220
	v_exp_f32_e32 v183, v183
	v_add_f32_e32 v201, v201, v205
	v_mul_f32_e32 v199, 0x3fb8aa3b, v199
	v_rcp_f32_e32 v177, v179
	v_rcp_f32_e32 v179, v143
	v_add_f32_e32 v220, v219, v201
	s_waitcnt lgkmcnt(0)
	v_add_f32_e32 v201, v201, v221
	v_exp_f32_e32 v218, v199
	v_add_f32_e32 v185, 1.0, v185
	v_mul_f32_e32 v199, 0x3fb8aa3b, v201
	v_rcp_f32_e32 v184, v186
	v_rcp_f32_e32 v186, v185
	v_rcp_f32_e32 v185, v187
	v_mul_f32_e32 v187, 0xbfb8aa3b, v95
	v_exp_f32_e32 v219, v199
	v_add_f32_e32 v183, 1.0, v183
	v_exp_f32_e32 v187, v187
	v_pk_mul_f32 v[178:179], v[126:127], v[178:179]
	v_rcp_f32_e32 v183, v183
	v_mul_f32_e32 v199, v212, v218
	v_pk_mul_f32 v[176:177], v[178:179], v[176:177]
	v_cvt_pk_bf16_f32 v199, v199, s0
	v_cvt_pk_bf16_f32 v189, v176, v177
	v_lshl_add_u64 v[176:177], s[44:45], 0, v[208:209]
	v_lshl_add_u64 v[178:179], s[48:49], 0, v[208:209]
	global_store_short v[206:207], v199, off
	v_mul_f32_e32 v199, v213, v219
	v_lshl_add_u64 v[176:177], v[176:177], 0, s[88:89]
	v_lshlrev_b32_e32 v152, 1, v154
	v_lshl_add_u64 v[178:179], v[178:179], 0, s[88:89]
	v_add_f32_e32 v187, 1.0, v187
	v_cvt_pk_bf16_f32 v199, v199, s0
	v_cvt_pk_bf16_f32 v143, v212, v213
	v_lshl_add_u64 v[176:177], v[176:177], 0, v[152:153]
	v_lshl_add_u64 v[178:179], v[178:179], 0, v[152:153]
	v_pk_mul_f32 v[182:183], v[110:111], v[182:183]
	v_rcp_f32_e32 v187, v187
	global_store_short v[206:207], v199, off offset:128
	global_store_dwordx2 v[176:177], v[188:189], off
	global_store_dwordx2 v[178:179], v[142:143], off
	v_mul_f32_e32 v142, v214, v218
	v_pk_mul_f32 v[180:181], v[182:183], v[180:181]
	v_or_b32_e32 v182, 0x8000, v208
	v_mov_b32_e32 v183, v209
	v_cvt_pk_bf16_f32 v142, v142, s0
	v_cvt_pk_bf16_f32 v197, v180, v181
	v_lshl_add_u64 v[180:181], s[44:45], 0, v[182:183]
	v_lshl_add_u64 v[182:183], s[48:49], 0, v[182:183]
	global_store_short v[206:207], v142, off offset:32
	v_mul_f32_e32 v142, v215, v219
	v_lshl_add_u64 v[180:181], v[180:181], 0, s[88:89]
	v_lshl_add_u64 v[182:183], v[182:183], 0, s[88:89]
	v_cvt_pk_bf16_f32 v142, v142, s0
	v_cvt_pk_bf16_f32 v191, v214, v215
	v_lshl_add_u64 v[180:181], v[180:181], 0, v[152:153]
	v_lshl_add_u64 v[182:183], v[182:183], 0, v[152:153]
	v_pk_mul_f32 v[186:187], v[94:95], v[186:187]
	global_store_short v[206:207], v142, off offset:160
	global_store_dwordx2 v[180:181], v[196:197], off
	global_store_dwordx2 v[182:183], v[190:191], off
	v_mul_f32_e32 v142, v216, v218
	v_pk_mul_f32 v[184:185], v[186:187], v[184:185]
	v_or_b32_e32 v186, 0x10000, v208
	v_mov_b32_e32 v187, v209
	v_cvt_pk_bf16_f32 v142, v142, s0
	v_cvt_pk_bf16_f32 v205, v184, v185
	v_lshl_add_u64 v[184:185], s[44:45], 0, v[186:187]
	v_lshl_add_u64 v[186:187], s[48:49], 0, v[186:187]
	global_store_short v[206:207], v142, off offset:64
	v_mul_f32_e32 v142, v217, v219
	v_lshl_add_u64 v[184:185], v[184:185], 0, s[88:89]
	v_lshl_add_u64 v[186:187], v[186:187], 0, s[88:89]
	v_cvt_pk_bf16_f32 v142, v142, s0
	v_cvt_pk_bf16_f32 v203, v216, v217
	v_lshl_add_u64 v[184:185], v[184:185], 0, v[152:153]
	v_lshl_add_u64 v[186:187], v[186:187], 0, v[152:153]
	global_store_short v[206:207], v142, off offset:192
	global_store_dwordx2 v[184:185], v[204:205], off
	global_store_dwordx2 v[186:187], v[202:203], off
	v_mul_f32_e32 v142, 0xbfb8aa3b, v238
	v_mul_f32_e32 v143, 0xbfb8aa3b, v220
	v_exp_f32_e32 v142, v142
	v_exp_f32_e32 v143, v143
	v_pk_add_f32 v[210:211], v[210:211], 1.0 op_sel_hi:[1,0] neg_lo:[1,0] neg_hi:[1,0]
	v_mul_f32_e32 v191, 0xbfb8aa3b, v79
	v_exp_f32_e32 v191, v191
	v_pk_mul_f32 v[188:189], v[210:211], v[142:143]
	v_rcp_f32_e32 v142, v142
	v_mul_f32_e32 v190, v218, v188
	v_cvt_pk_bf16_f32 v190, v190, s0
	global_store_short v[206:207], v190, off offset:96
	v_mul_f32_e32 v190, v219, v189
	v_cvt_pk_bf16_f32 v190, v190, s0
	global_store_short v[206:207], v190, off offset:224
	v_mul_f32_e32 v190, 0xbfb8aa3b, v78
	v_exp_f32_e32 v190, v190
	v_add_f32_e32 v191, 1.0, v191
	v_rcp_f32_e32 v191, v191
	v_rcp_f32_e32 v143, v143
	v_add_f32_e32 v190, 1.0, v190
	v_rcp_f32_e32 v190, v190
	v_or_b32_e32 v208, 0x18000, v208
	v_cvt_pk_bf16_f32 v199, v188, v189
	v_pk_mul_f32 v[190:191], v[78:79], v[190:191]
	s_nop 0
	v_pk_mul_f32 v[142:143], v[190:191], v[142:143]
	s_nop 0
	v_cvt_pk_bf16_f32 v201, v142, v143
	v_lshl_add_u64 v[142:143], s[44:45], 0, v[208:209]
	v_lshl_add_u64 v[142:143], v[142:143], 0, s[88:89]
	v_lshl_add_u64 v[188:189], v[142:143], 0, v[152:153]
	v_lshl_add_u64 v[142:143], s[48:49], 0, v[208:209]
	v_lshl_add_u64 v[142:143], v[142:143], 0, s[88:89]
	v_lshl_add_u64 v[190:191], v[142:143], 0, v[152:153]
	global_store_dwordx2 v[188:189], v[200:201], off
	global_store_dwordx2 v[190:191], v[198:199], off
	s_and_saveexec_b64 s[14:15], s[4:5]
	s_cbranch_execz .LBB0_1950
	s_add_u32 s28, s33, s94
	s_addc_u32 s29, s0, s95
	s_lshl_b64 vcc, s[86:87], 2
	s_add_u32 vcc_lo, s28, vcc_lo
	s_addc_u32 vcc_hi, s29, vcc_hi
	global_store_dwordx2 v237, v[218:219], vcc offset:8
.LBB0_1950:
	s_or_b64 exec, exec, s[14:15]
	v_sub_f32_e32 v128, v128, v132
	v_mul_f32_e32 v128, 0x3fb8aa3b, v128
	v_exp_f32_e32 v128, v128
	s_nop 0
	v_add_f32_e32 v128, 1.0, v128
	v_rcp_f32_e32 v132, v128
	v_sub_f32_e32 v128, v129, v133
	v_mul_f32_e32 v128, 0x3fb8aa3b, v128
	v_exp_f32_e32 v128, v128
	v_mov_b32_e32 v129, s85
	v_add_f32_e32 v128, 1.0, v128
	v_rcp_f32_e32 v133, v128
	v_mul_f32_e32 v128, 0xbfb8aa3b, v112
	v_exp_f32_e32 v128, v128
	v_pk_add_f32 v[142:143], v[132:133], 1.0 op_sel_hi:[1,0] neg_lo:[1,0] neg_hi:[1,0]
	v_add_f32_e32 v128, 1.0, v128
	v_rcp_f32_e32 v196, v128
	v_mul_f32_e32 v128, 0xbfb8aa3b, v113
	v_exp_f32_e32 v128, v128
	s_nop 0
	v_add_f32_e32 v128, 1.0, v128
	v_rcp_f32_e32 v197, v128
	v_mul_f32_e32 v128, 0xbfb8aa3b, v96
	v_exp_f32_e32 v128, v128
	v_pk_fma_f32 v[196:197], v[196:197], v[142:143], v[132:133]
	s_nop 0
	v_cmp_gt_f32_e32 vcc, s47, v196
	v_add_f32_e32 v128, 1.0, v128
	v_rcp_f32_e32 v202, v128
	v_cndmask_b32_e64 v198, 0, 32, vcc
	v_ldexp_f32 v198, v196, v198
	v_log_f32_e32 v198, v198
	v_mul_f32_e32 v128, 0xbfb8aa3b, v97
	v_exp_f32_e32 v128, v128
	v_mul_f32_e32 v199, 0x3f317217, v198
	v_fma_f32 v199, v198, s96, -v199
	v_fmac_f32_e32 v199, 0x3377d1cf, v198
	v_fmac_f32_e32 v199, 0x3f317217, v198
	v_cmp_lt_f32_e64 s[14:15], |v198|, s1
	v_add_f32_e32 v128, 1.0, v128
	v_rcp_f32_e32 v203, v128
	v_cndmask_b32_e64 v198, v198, v199, s[14:15]
	v_cndmask_b32_e32 v199, 0, v223, vcc
	v_cmp_gt_f32_e32 vcc, s47, v197
	v_sub_f32_e32 v198, v198, v199
	v_pk_fma_f32 v[202:203], v[202:203], v[142:143], v[132:133]
	v_cndmask_b32_e64 v199, 0, 32, vcc
	v_ldexp_f32 v199, v197, v199
	v_log_f32_e32 v199, v199
	v_mul_f32_e32 v128, 0xbfb8aa3b, v80
	v_exp_f32_e32 v128, v128
	v_pk_add_f32 v[196:197], v[196:197], 1.0 op_sel_hi:[1,0] neg_lo:[1,0] neg_hi:[1,0]
	v_mul_f32_e32 v204, 0x3f317217, v199
	v_fma_f32 v204, v199, s96, -v204
	v_fmac_f32_e32 v204, 0x3377d1cf, v199
	v_fmac_f32_e32 v204, 0x3f317217, v199
	v_cmp_lt_f32_e64 s[14:15], |v199|, s1
	v_add_f32_e32 v128, 1.0, v128
	v_rcp_f32_e32 v206, v128
	v_cndmask_b32_e64 v199, v199, v204, s[14:15]
	v_cndmask_b32_e32 v204, 0, v223, vcc
	v_sub_f32_e32 v199, v199, v204
	v_cmp_gt_f32_e32 vcc, s47, v202
	v_mul_f32_e32 v128, 0xbfb8aa3b, v81
	v_exp_f32_e32 v128, v128
	s_waitcnt lgkmcnt(0)
	s_nop 1
	v_add_f32_dpp v198, v198, v198 row_shr:1 row_mask:0xf bank_mask:0xf
	v_add_f32_e32 v128, 1.0, v128
	v_rcp_f32_e32 v207, v128
	v_mul_f32_e32 v128, 0xbfb8aa3b, v64
	v_exp_f32_e32 v128, v128
	s_waitcnt lgkmcnt(0)
	s_nop 1
	v_add_f32_dpp v199, v199, v199 row_shr:1 row_mask:0xf bank_mask:0xf
	v_pk_fma_f32 v[206:207], v[206:207], v[142:143], v[132:133]
	v_add_f32_e32 v128, 1.0, v128
	v_rcp_f32_e32 v200, v128
	v_mul_f32_e32 v128, 0xbfb8aa3b, v65
	s_waitcnt lgkmcnt(0)
	s_nop 1
	v_add_f32_dpp v198, v198, v198 row_shr:2 row_mask:0xf bank_mask:0xf
	v_exp_f32_e32 v128, v128
	s_waitcnt lgkmcnt(0)
	s_nop 1
	v_add_f32_dpp v199, v199, v199 row_shr:2 row_mask:0xf bank_mask:0xf
	v_add_f32_e32 v128, 1.0, v128
	v_rcp_f32_e32 v201, v128
	v_or_b32_e32 v128, s67, v160
	v_lshlrev_b64 v[128:129], 7, v[128:129]
	s_waitcnt lgkmcnt(0)
	s_nop 1
	v_add_f32_dpp v198, v198, v198 row_shr:4 row_mask:0xf bank_mask:0xf
	v_pk_fma_f32 v[200:201], v[200:201], v[142:143], v[132:133]
	v_lshl_add_u64 v[128:129], v[164:165], 0, v[128:129]
	s_waitcnt lgkmcnt(0)
	s_nop 1
	v_add_f32_dpp v199, v199, v199 row_shr:4 row_mask:0xf bank_mask:0xf
	s_waitcnt lgkmcnt(0)
	s_nop 1
	v_add_f32_dpp v198, v198, v198 row_shr:8 row_mask:0xf bank_mask:0xf
	s_waitcnt lgkmcnt(0)
	s_nop 1
	v_add_f32_dpp v199, v199, v199 row_shr:8 row_mask:0xf bank_mask:0xf
	s_nop 1
	v_mov_b32_dpp v204, v198 row_newbcast:15 row_mask:0xf bank_mask:0xf
	v_add_f32_e32 v198, 0, v198
	v_mul_f32_e32 v198, 0xbfb8aa3b, v198
	v_exp_f32_e32 v198, v198
	s_waitcnt lgkmcnt(0)
	v_add_f32_e32 v208, 0, v204
	s_nop 1
	v_mov_b32_dpp v204, v199 row_newbcast:15 row_mask:0xf bank_mask:0xf
	v_add_f32_e32 v199, 0, v199
	v_mul_f32_e32 v199, 0xbfb8aa3b, v199
	v_exp_f32_e32 v199, v199
	s_waitcnt lgkmcnt(0)
	v_add_f32_e32 v209, 0, v204
	v_cndmask_b32_e64 v204, 0, 32, vcc
	v_ldexp_f32 v204, v202, v204
	v_log_f32_e32 v204, v204
	v_pk_mul_f32 v[196:197], v[196:197], v[198:199]
	v_mul_f32_e32 v205, 0x3f317217, v204
	v_fma_f32 v205, v204, s96, -v205
	v_fmac_f32_e32 v205, 0x3377d1cf, v204
	v_fmac_f32_e32 v205, 0x3f317217, v204
	v_cmp_lt_f32_e64 s[14:15], |v204|, s1
	s_nop 1
	v_cndmask_b32_e64 v204, v204, v205, s[14:15]
	v_cndmask_b32_e32 v205, 0, v223, vcc
	v_cmp_gt_f32_e32 vcc, s47, v203
	v_sub_f32_e32 v210, v204, v205
	s_nop 0
	v_cndmask_b32_e64 v204, 0, 32, vcc
	v_ldexp_f32 v204, v203, v204
	v_log_f32_e32 v204, v204
	s_nop 0
	v_mul_f32_e32 v205, 0x3f317217, v204
	v_fma_f32 v205, v204, s96, -v205
	v_fmac_f32_e32 v205, 0x3377d1cf, v204
	v_fmac_f32_e32 v205, 0x3f317217, v204
	v_cmp_lt_f32_e64 s[14:15], |v204|, s1
	s_nop 1
	v_cndmask_b32_e64 v204, v204, v205, s[14:15]
	v_cndmask_b32_e32 v205, 0, v223, vcc
	v_sub_f32_e32 v211, v204, v205
	v_pk_add_f32 v[204:205], v[202:203], 1.0 op_sel_hi:[1,0] neg_lo:[1,0] neg_hi:[1,0]
	v_cmp_gt_f32_e32 vcc, s47, v206
	s_waitcnt lgkmcnt(1)
	v_mov_b32_e32 v202, v210
	s_nop 1
	v_add_f32_dpp v202, v210, v210 row_shr:1 row_mask:0xf bank_mask:0xf
	s_waitcnt lgkmcnt(1)
	v_mov_b32_e32 v203, v211
	s_nop 1
	v_add_f32_dpp v203, v211, v211 row_shr:1 row_mask:0xf bank_mask:0xf
	s_waitcnt lgkmcnt(0)
	s_nop 1
	v_add_f32_dpp v202, v202, v202 row_shr:2 row_mask:0xf bank_mask:0xf
	s_waitcnt lgkmcnt(0)
	s_nop 1
	v_add_f32_dpp v203, v203, v203 row_shr:2 row_mask:0xf bank_mask:0xf
	s_waitcnt lgkmcnt(0)
	s_nop 1
	v_add_f32_dpp v202, v202, v202 row_shr:4 row_mask:0xf bank_mask:0xf
	s_waitcnt lgkmcnt(0)
	s_nop 1
	v_add_f32_dpp v203, v203, v203 row_shr:4 row_mask:0xf bank_mask:0xf
	s_waitcnt lgkmcnt(0)
	s_nop 1
	v_add_f32_dpp v202, v202, v202 row_shr:8 row_mask:0xf bank_mask:0xf
	s_waitcnt lgkmcnt(0)
	s_nop 1
	v_add_f32_dpp v203, v203, v203 row_shr:8 row_mask:0xf bank_mask:0xf
	s_nop 1
	v_mov_b32_dpp v210, v202 row_newbcast:15 row_mask:0xf bank_mask:0xf
	v_add_f32_e32 v202, v202, v208
	s_nop 1
	v_mov_b32_dpp v211, v203 row_newbcast:15 row_mask:0xf bank_mask:0xf
	v_add_f32_e32 v203, v203, v209
	v_mul_f32_e32 v202, 0xbfb8aa3b, v202
	s_waitcnt lgkmcnt(1)
	v_add_f32_e32 v208, v208, v210
	v_cndmask_b32_e64 v210, 0, 32, vcc
	v_ldexp_f32 v210, v206, v210
	v_log_f32_e32 v210, v210
	s_waitcnt lgkmcnt(0)
	v_add_f32_e32 v209, v209, v211
	v_mul_f32_e32 v203, 0xbfb8aa3b, v203
	v_exp_f32_e32 v202, v202
	v_mul_f32_e32 v211, 0x3f317217, v210
	v_fma_f32 v211, v210, s96, -v211
	v_fmac_f32_e32 v211, 0x3377d1cf, v210
	v_fmac_f32_e32 v211, 0x3f317217, v210
	v_cmp_lt_f32_e64 s[14:15], |v210|, s1
	v_exp_f32_e32 v203, v203
	s_nop 0
	v_cndmask_b32_e64 v210, v210, v211, s[14:15]
	v_cndmask_b32_e32 v211, 0, v223, vcc
	v_cmp_gt_f32_e32 vcc, s47, v207
	v_sub_f32_e32 v210, v210, v211
	v_pk_mul_f32 v[204:205], v[204:205], v[202:203]
	v_cndmask_b32_e64 v211, 0, 32, vcc
	v_ldexp_f32 v211, v207, v211
	v_log_f32_e32 v211, v211
	v_pk_add_f32 v[206:207], v[206:207], 1.0 op_sel_hi:[1,0] neg_lo:[1,0] neg_hi:[1,0]
	v_mul_f32_e32 v212, 0x3f317217, v211
	v_fma_f32 v212, v211, s96, -v212
	v_fmac_f32_e32 v212, 0x3377d1cf, v211
	v_fmac_f32_e32 v212, 0x3f317217, v211
	v_cmp_lt_f32_e64 s[14:15], |v211|, s1
	s_nop 1
	v_cndmask_b32_e64 v211, v211, v212, s[14:15]
	v_cndmask_b32_e32 v212, 0, v223, vcc
	v_sub_f32_e32 v211, v211, v212
	v_cmp_gt_f32_e32 vcc, s47, v200
	s_waitcnt lgkmcnt(0)
	s_nop 1
	v_add_f32_dpp v210, v210, v210 row_shr:1 row_mask:0xf bank_mask:0xf
	s_waitcnt lgkmcnt(0)
	s_nop 1
	v_add_f32_dpp v211, v211, v211 row_shr:1 row_mask:0xf bank_mask:0xf
	s_waitcnt lgkmcnt(0)
	s_nop 1
	v_add_f32_dpp v210, v210, v210 row_shr:2 row_mask:0xf bank_mask:0xf
	s_waitcnt lgkmcnt(0)
	s_nop 1
	v_add_f32_dpp v211, v211, v211 row_shr:2 row_mask:0xf bank_mask:0xf
	s_waitcnt lgkmcnt(0)
	s_nop 1
	v_add_f32_dpp v210, v210, v210 row_shr:4 row_mask:0xf bank_mask:0xf
	s_waitcnt lgkmcnt(0)
	s_nop 1
	v_add_f32_dpp v211, v211, v211 row_shr:4 row_mask:0xf bank_mask:0xf
	s_waitcnt lgkmcnt(0)
	s_nop 1
	v_add_f32_dpp v210, v210, v210 row_shr:8 row_mask:0xf bank_mask:0xf
	s_waitcnt lgkmcnt(0)
	s_nop 1
	v_add_f32_dpp v211, v211, v211 row_shr:8 row_mask:0xf bank_mask:0xf
	s_nop 1
	v_mov_b32_dpp v212, v210 row_newbcast:15 row_mask:0xf bank_mask:0xf
	v_add_f32_e32 v210, v210, v208
	s_nop 1
	v_mov_b32_dpp v213, v211 row_newbcast:15 row_mask:0xf bank_mask:0xf
	v_add_f32_e32 v211, v211, v209
	s_waitcnt lgkmcnt(1)
	v_add_f32_e32 v212, v208, v212
	v_mul_f32_e32 v208, 0xbfb8aa3b, v210
	v_cndmask_b32_e64 v210, 0, 32, vcc
	v_ldexp_f32 v210, v200, v210
	v_log_f32_e32 v210, v210
	s_waitcnt lgkmcnt(0)
	v_add_f32_e32 v213, v209, v213
	v_mul_f32_e32 v209, 0xbfb8aa3b, v211
	v_exp_f32_e32 v208, v208
	v_mul_f32_e32 v211, 0x3f317217, v210
	v_fma_f32 v211, v210, s96, -v211
	v_fmac_f32_e32 v211, 0x3377d1cf, v210
	v_fmac_f32_e32 v211, 0x3f317217, v210
	v_cmp_lt_f32_e64 s[14:15], |v210|, s1
	v_exp_f32_e32 v209, v209
	s_nop 0
	v_cndmask_b32_e64 v210, v210, v211, s[14:15]
	v_cndmask_b32_e32 v211, 0, v223, vcc
	v_cmp_gt_f32_e32 vcc, s47, v201
	v_sub_f32_e32 v210, v210, v211
	v_pk_mul_f32 v[206:207], v[206:207], v[208:209]
	v_cndmask_b32_e64 v211, 0, 32, vcc
	v_ldexp_f32 v211, v201, v211
	v_log_f32_e32 v211, v211
	v_pk_add_f32 v[200:201], v[200:201], 1.0 op_sel_hi:[1,0] neg_lo:[1,0] neg_hi:[1,0]
	v_mul_f32_e32 v214, 0x3f317217, v211
	v_fma_f32 v214, v211, s96, -v214
	v_fmac_f32_e32 v214, 0x3377d1cf, v211
	v_fmac_f32_e32 v214, 0x3f317217, v211
	v_cmp_lt_f32_e64 s[14:15], |v211|, s1
	s_nop 1
	v_cndmask_b32_e64 v211, v211, v214, s[14:15]
	v_cndmask_b32_e32 v214, 0, v223, vcc
	v_sub_f32_e32 v211, v211, v214
	s_waitcnt lgkmcnt(0)
	s_nop 1
	v_add_f32_dpp v210, v210, v210 row_shr:1 row_mask:0xf bank_mask:0xf
	s_waitcnt lgkmcnt(0)
	s_nop 1
	v_add_f32_dpp v211, v211, v211 row_shr:1 row_mask:0xf bank_mask:0xf
	s_waitcnt lgkmcnt(0)
	s_nop 1
	v_add_f32_dpp v210, v210, v210 row_shr:2 row_mask:0xf bank_mask:0xf
	s_waitcnt lgkmcnt(0)
	s_nop 1
	v_add_f32_dpp v211, v211, v211 row_shr:2 row_mask:0xf bank_mask:0xf
	s_waitcnt lgkmcnt(0)
	s_nop 1
	v_add_f32_dpp v210, v210, v210 row_shr:4 row_mask:0xf bank_mask:0xf
	s_waitcnt lgkmcnt(0)
	s_nop 1
	v_add_f32_dpp v211, v211, v211 row_shr:4 row_mask:0xf bank_mask:0xf
	s_waitcnt lgkmcnt(0)
	s_nop 1
	v_add_f32_dpp v210, v210, v210 row_shr:8 row_mask:0xf bank_mask:0xf
	v_add_f32_e32 v216, v210, v212
	s_waitcnt lgkmcnt(0)
	s_nop 1
	v_add_f32_dpp v211, v211, v211 row_shr:8 row_mask:0xf bank_mask:0xf
	s_nop 1
	v_mov_b32_dpp v214, v210 row_newbcast:15 row_mask:0xf bank_mask:0xf
	s_nop 1
	v_mov_b32_dpp v215, v211 row_newbcast:15 row_mask:0xf bank_mask:0xf
	s_waitcnt lgkmcnt(1)
	v_add_f32_e32 v210, v212, v214
	v_mul_f32_e32 v210, 0x3fb8aa3b, v210
	v_add_f32_e32 v212, v211, v213
	s_waitcnt lgkmcnt(0)
	v_add_f32_e32 v211, v213, v215
	v_exp_f32_e32 v210, v210
	v_mul_f32_e32 v211, 0x3fb8aa3b, v211
	v_exp_f32_e32 v211, v211
	v_mul_f32_e32 v212, 0xbfb8aa3b, v212
	v_mul_f32_e32 v213, v196, v210
	v_cvt_pk_bf16_f32 v213, v213, s0
	global_store_short v[128:129], v213, off
	v_mul_f32_e32 v213, v197, v211
	v_cvt_pk_bf16_f32 v213, v213, s0
	global_store_short v[128:129], v213, off offset:128
	v_mul_f32_e32 v213, v204, v210
	v_cvt_pk_bf16_f32 v213, v213, s0
	global_store_short v[128:129], v213, off offset:32
	v_mul_f32_e32 v213, v205, v211
	v_cvt_pk_bf16_f32 v213, v213, s0
	global_store_short v[128:129], v213, off offset:160
	v_mul_f32_e32 v213, v206, v210
	v_cvt_pk_bf16_f32 v213, v213, s0
	global_store_short v[128:129], v213, off offset:64
	v_mul_f32_e32 v213, v207, v211
	v_cvt_pk_bf16_f32 v213, v213, s0
	global_store_short v[128:129], v213, off offset:192
	v_mul_f32_e32 v213, 0xbfb8aa3b, v216
	v_exp_f32_e32 v214, v213
	v_exp_f32_e32 v215, v212
	s_nop 0
	v_pk_mul_f32 v[212:213], v[200:201], v[214:215]
	s_nop 0
	v_mul_f32_e32 v200, v210, v212
	v_cvt_pk_bf16_f32 v200, v200, s0
	global_store_short v[128:129], v200, off offset:96
	v_mul_f32_e32 v200, v211, v213
	v_cvt_pk_bf16_f32 v200, v200, s0
	global_store_short v[128:129], v200, off offset:224
	s_and_saveexec_b64 s[14:15], s[4:5]
	s_cbranch_execz .LBB0_1952
	s_add_u32 s28, s33, s94
	s_addc_u32 s29, s0, s95
	s_lshl_b64 vcc, s[86:87], 2
	s_add_u32 vcc_lo, s28, vcc_lo
	s_addc_u32 vcc_hi, s29, vcc_hi
	global_store_dwordx2 v237, v[210:211], vcc offset:16
.LBB0_1952:
	s_or_b64 exec, exec, s[14:15]
	v_mul_f32_e32 v129, 0xbfb8aa3b, v120
	v_exp_f32_e32 v129, v129
	v_rcp_f32_e32 v128, v198
	v_cvt_pk_bf16_f32 v196, v196, v197
	v_mul_f32_e32 v197, 0xbfb8aa3b, v105
	v_add_f32_e32 v129, 1.0, v129
	v_rcp_f32_e32 v198, v129
	v_rcp_f32_e32 v129, v199
	v_mul_f32_e32 v199, 0xbfb8aa3b, v121
	v_exp_f32_e32 v199, v199
	v_exp_f32_e32 v197, v197
	v_add_f32_e32 v199, 1.0, v199
	v_rcp_f32_e32 v199, v199
	v_add_f32_e32 v197, 1.0, v197
	v_rcp_f32_e32 v201, v197
	v_mul_f32_e32 v197, 0xbfb8aa3b, v89
	v_pk_mul_f32 v[198:199], v[120:121], v[198:199]
	v_exp_f32_e32 v197, v197
	v_pk_mul_f32 v[128:129], v[198:199], v[128:129]
	v_add_f32_e32 v197, 1.0, v197
	v_cvt_pk_bf16_f32 v198, v128, v129
	v_mul_f32_e32 v129, 0xbfb8aa3b, v104
	v_exp_f32_e32 v129, v129
	v_rcp_f32_e32 v128, v202
	v_add_f32_e32 v129, 1.0, v129
	v_rcp_f32_e32 v200, v129
	v_rcp_f32_e32 v129, v203
	v_pk_mul_f32 v[200:201], v[104:105], v[200:201]
	s_nop 0
	v_pk_mul_f32 v[128:129], v[200:201], v[128:129]
	v_cvt_pk_bf16_f32 v200, v204, v205
	v_cvt_pk_bf16_f32 v202, v128, v129
	v_mul_f32_e32 v129, 0xbfb8aa3b, v88
	v_exp_f32_e32 v129, v129
	v_rcp_f32_e32 v205, v197
	v_rcp_f32_e32 v128, v208
	v_mul_f32_e32 v197, 0xbfb8aa3b, v73
	v_add_f32_e32 v129, 1.0, v129
	v_rcp_f32_e32 v204, v129
	v_rcp_f32_e32 v129, v209
	v_exp_f32_e32 v197, v197
	v_cvt_pk_bf16_f32 v208, v206, v207
	v_pk_mul_f32 v[204:205], v[88:89], v[204:205]
	v_add_f32_e32 v197, 1.0, v197
	v_pk_mul_f32 v[128:129], v[204:205], v[128:129]
	v_rcp_f32_e32 v205, v197
	v_cvt_pk_bf16_f32 v210, v128, v129
	v_mul_f32_e32 v129, 0xbfb8aa3b, v72
	v_exp_f32_e32 v129, v129
	v_rcp_f32_e32 v128, v214
	v_add_f32_e32 v129, 1.0, v129
	v_rcp_f32_e32 v204, v129
	v_rcp_f32_e32 v129, v215
	v_pk_mul_f32 v[204:205], v[72:73], v[204:205]
	s_nop 0
	v_pk_mul_f32 v[128:129], v[204:205], v[128:129]
	v_cvt_pk_bf16_f32 v204, v212, v213
	v_cvt_pk_bf16_f32 v206, v128, v129
	v_sub_f32_e32 v128, v130, v134
	v_mul_f32_e32 v134, 0xbfb8aa3b, v114
	v_exp_f32_e32 v134, v134
	v_sub_f32_e32 v129, v131, v135
	v_mul_f32_e32 v128, 0x3fb8aa3b, v128
	v_mul_f32_e32 v129, 0x3fb8aa3b, v129
	v_add_f32_e32 v134, 1.0, v134
	v_exp_f32_e32 v128, v128
	v_exp_f32_e32 v129, v129
	v_rcp_f32_e32 v214, v134
	v_mul_f32_e32 v134, 0xbfb8aa3b, v115
	v_exp_f32_e32 v134, v134
	v_add_f32_e32 v128, 1.0, v128
	v_add_f32_e32 v129, 1.0, v129
	v_rcp_f32_e32 v128, v128
	v_rcp_f32_e32 v129, v129
	v_add_f32_e32 v134, 1.0, v134
	v_rcp_f32_e32 v215, v134
	v_mul_f32_e32 v134, 0xbfb8aa3b, v98
	v_pk_add_f32 v[130:131], v[128:129], 1.0 op_sel_hi:[1,0] neg_lo:[1,0] neg_hi:[1,0]
	v_exp_f32_e32 v134, v134
	v_pk_fma_f32 v[214:215], v[214:215], v[130:131], v[128:129]
	v_mov_b32_e32 v135, s85
	v_cmp_gt_f32_e32 vcc, s47, v214
	v_add_f32_e32 v134, 1.0, v134
	v_rcp_f32_e32 v218, v134
	v_cndmask_b32_e64 v197, 0, 32, vcc
	v_ldexp_f32 v197, v214, v197
	v_log_f32_e32 v197, v197
	v_mul_f32_e32 v134, 0xbfb8aa3b, v99
	v_exp_f32_e32 v134, v134
	v_mul_f32_e32 v199, 0x3f317217, v197
	v_fma_f32 v199, v197, s96, -v199
	v_fmac_f32_e32 v199, 0x3377d1cf, v197
	v_fmac_f32_e32 v199, 0x3f317217, v197
	v_cmp_lt_f32_e64 s[14:15], |v197|, s1
	v_add_f32_e32 v134, 1.0, v134
	v_rcp_f32_e32 v219, v134
	v_cndmask_b32_e64 v197, v197, v199, s[14:15]
	v_cndmask_b32_e32 v199, 0, v223, vcc
	v_cmp_gt_f32_e32 vcc, s47, v215
	v_sub_f32_e32 v197, v197, v199
	v_pk_fma_f32 v[218:219], v[218:219], v[130:131], v[128:129]
	v_cndmask_b32_e64 v199, 0, 32, vcc
	v_ldexp_f32 v199, v215, v199
	v_log_f32_e32 v199, v199
	v_mul_f32_e32 v134, 0xbfb8aa3b, v82
	v_exp_f32_e32 v134, v134
	v_pk_add_f32 v[214:215], v[214:215], 1.0 op_sel_hi:[1,0] neg_lo:[1,0] neg_hi:[1,0]
	v_mul_f32_e32 v201, 0x3f317217, v199
	v_fma_f32 v201, v199, s96, -v201
	v_fmac_f32_e32 v201, 0x3377d1cf, v199
	v_fmac_f32_e32 v201, 0x3f317217, v199
	v_cmp_lt_f32_e64 s[14:15], |v199|, s1
	v_add_f32_e32 v134, 1.0, v134
	v_rcp_f32_e32 v216, v134
	v_cndmask_b32_e64 v199, v199, v201, s[14:15]
	v_cndmask_b32_e32 v201, 0, v223, vcc
	v_cmp_gt_f32_e32 vcc, s47, v218
	v_sub_f32_e32 v199, v199, v201
	v_cndmask_b32_e64 v205, 0, 32, vcc
	v_ldexp_f32 v205, v218, v205
	v_log_f32_e32 v205, v205
	v_mul_f32_e32 v134, 0xbfb8aa3b, v83
	s_waitcnt lgkmcnt(0)
	s_nop 1
	v_add_f32_dpp v197, v197, v197 row_shr:1 row_mask:0xf bank_mask:0xf
	v_mul_f32_e32 v207, 0x3f317217, v205
	v_fma_f32 v207, v205, s96, -v207
	v_fmac_f32_e32 v207, 0x3377d1cf, v205
	v_fmac_f32_e32 v207, 0x3f317217, v205
	v_cmp_lt_f32_e64 s[14:15], |v205|, s1
	v_exp_f32_e32 v134, v134
	v_cndmask_b32_e64 v205, v205, v207, s[14:15]
	v_cndmask_b32_e32 v207, 0, v223, vcc
	v_cmp_gt_f32_e32 vcc, s47, v219
	v_sub_f32_e32 v205, v205, v207
	s_waitcnt lgkmcnt(0)
	v_cndmask_b32_e64 v207, 0, 32, vcc
	v_ldexp_f32 v207, v219, v207
	v_log_f32_e32 v207, v207
	s_nop 1
	v_add_f32_dpp v199, v199, v199 row_shr:1 row_mask:0xf bank_mask:0xf
	v_add_f32_e32 v134, 1.0, v134
	v_mul_f32_e32 v209, 0x3f317217, v207
	v_fma_f32 v209, v207, s96, -v209
	v_fmac_f32_e32 v209, 0x3377d1cf, v207
	v_fmac_f32_e32 v209, 0x3f317217, v207
	v_cmp_lt_f32_e64 s[14:15], |v207|, s1
	s_waitcnt lgkmcnt(0)
	s_nop 1
	v_add_f32_dpp v197, v197, v197 row_shr:2 row_mask:0xf bank_mask:0xf
	v_cndmask_b32_e64 v207, v207, v209, s[14:15]
	v_cndmask_b32_e32 v209, 0, v223, vcc
	v_sub_f32_e32 v207, v207, v209
	v_rcp_f32_e32 v217, v134
	v_pk_add_f32 v[218:219], v[218:219], 1.0 op_sel_hi:[1,0] neg_lo:[1,0] neg_hi:[1,0]
	v_mul_f32_e32 v134, 0xbfb8aa3b, v66
	s_waitcnt lgkmcnt(1)
	s_nop 1
	v_add_f32_dpp v205, v205, v205 row_shr:1 row_mask:0xf bank_mask:0xf
	s_waitcnt lgkmcnt(1)
	s_nop 1
	v_add_f32_dpp v199, v199, v199 row_shr:2 row_mask:0xf bank_mask:0xf
	v_pk_fma_f32 v[216:217], v[216:217], v[130:131], v[128:129]
	s_waitcnt lgkmcnt(1)
	s_nop 1
	v_add_f32_dpp v207, v207, v207 row_shr:1 row_mask:0xf bank_mask:0xf
	s_waitcnt lgkmcnt(1)
	s_nop 1
	v_add_f32_dpp v197, v197, v197 row_shr:4 row_mask:0xf bank_mask:0xf
	v_cmp_gt_f32_e32 vcc, s47, v216
	s_waitcnt lgkmcnt(1)
	s_nop 1
	v_add_f32_dpp v205, v205, v205 row_shr:2 row_mask:0xf bank_mask:0xf
	s_waitcnt lgkmcnt(1)
	s_nop 1
	v_add_f32_dpp v199, v199, v199 row_shr:4 row_mask:0xf bank_mask:0xf
	v_exp_f32_e32 v134, v134
	s_waitcnt lgkmcnt(1)
	s_nop 1
	v_add_f32_dpp v207, v207, v207 row_shr:2 row_mask:0xf bank_mask:0xf
	s_waitcnt lgkmcnt(1)
	s_nop 1
	v_add_f32_dpp v197, v197, v197 row_shr:8 row_mask:0xf bank_mask:0xf
	v_add_f32_e32 v134, 1.0, v134
	s_waitcnt lgkmcnt(1)
	s_nop 1
	v_add_f32_dpp v205, v205, v205 row_shr:4 row_mask:0xf bank_mask:0xf
	s_waitcnt lgkmcnt(1)
	s_nop 1
	v_add_f32_dpp v199, v199, v199 row_shr:8 row_mask:0xf bank_mask:0xf
	s_nop 1
	v_mov_b32_dpp v201, v197 row_newbcast:15 row_mask:0xf bank_mask:0xf
	v_add_f32_e32 v197, 0, v197
	s_nop 1
	v_mov_b32_dpp v203, v199 row_newbcast:15 row_mask:0xf bank_mask:0xf
	v_add_f32_e32 v199, 0, v199
	v_mul_f32_e32 v197, 0xbfb8aa3b, v197
	s_waitcnt lgkmcnt(2)
	v_exp_f32_e32 v220, v197
	v_mul_f32_e32 v197, 0xbfb8aa3b, v199
	s_nop 1
	v_add_f32_dpp v207, v207, v207 row_shr:4 row_mask:0xf bank_mask:0xf
	v_exp_f32_e32 v221, v197
	v_mul_f32_e32 v197, 0xbfb8aa3b, v122
	v_exp_f32_e32 v197, v197
	s_waitcnt lgkmcnt(2)
	v_add_f32_e32 v201, 0, v201
	s_waitcnt lgkmcnt(0)
	s_nop 1
	v_add_f32_dpp v205, v205, v205 row_shr:8 row_mask:0xf bank_mask:0xf
	v_add_f32_e32 v197, 1.0, v197
	v_rcp_f32_e32 v238, v197
	v_mul_f32_e32 v197, 0xbfb8aa3b, v123
	v_exp_f32_e32 v197, v197
	v_pk_mul_f32 v[214:215], v[214:215], v[220:221]
	s_waitcnt lgkmcnt(0)
	s_nop 1
	v_add_f32_dpp v207, v207, v207 row_shr:8 row_mask:0xf bank_mask:0xf
	v_add_f32_e32 v197, 1.0, v197
	s_nop 1
	v_mov_b32_dpp v209, v205 row_newbcast:15 row_mask:0xf bank_mask:0xf
	v_rcp_f32_e32 v239, v197
	v_rcp_f32_e32 v220, v220
	v_rcp_f32_e32 v221, v221
	s_nop 1
	v_mov_b32_dpp v211, v207 row_newbcast:15 row_mask:0xf bank_mask:0xf
	v_add_f32_e32 v203, 0, v203
	v_pk_mul_f32 v[238:239], v[122:123], v[238:239]
	v_add_f32_e32 v205, v205, v201
	s_waitcnt lgkmcnt(1)
	v_add_f32_e32 v209, v201, v209
	v_add_f32_e32 v201, v207, v203
	v_pk_mul_f32 v[220:221], v[238:239], v[220:221]
	v_mul_f32_e32 v201, 0xbfb8aa3b, v201
	v_cvt_pk_bf16_f32 v199, v220, v221
	v_exp_f32_e32 v221, v201
	v_mul_f32_e32 v201, 0xbfb8aa3b, v106
	s_waitcnt lgkmcnt(0)
	v_add_f32_e32 v207, v203, v211
	v_mul_f32_e32 v203, 0xbfb8aa3b, v205
	v_exp_f32_e32 v201, v201
	v_cndmask_b32_e64 v205, 0, 32, vcc
	v_ldexp_f32 v205, v216, v205
	v_log_f32_e32 v205, v205
	v_add_f32_e32 v201, 1.0, v201
	v_rcp_f32_e32 v238, v201
	v_mul_f32_e32 v201, 0xbfb8aa3b, v107
	v_exp_f32_e32 v201, v201
	v_mul_f32_e32 v211, 0x3f317217, v205
	v_fma_f32 v211, v205, s96, -v211
	v_exp_f32_e32 v220, v203
	v_fmac_f32_e32 v211, 0x3377d1cf, v205
	v_fmac_f32_e32 v211, 0x3f317217, v205
	v_cmp_lt_f32_e64 s[14:15], |v205|, s1
	v_add_f32_e32 v201, 1.0, v201
	v_rcp_f32_e32 v239, v201
	v_cndmask_b32_e64 v205, v205, v211, s[14:15]
	v_cndmask_b32_e32 v211, 0, v223, vcc
	v_cmp_gt_f32_e32 vcc, s47, v217
	v_sub_f32_e32 v205, v205, v211
	v_pk_mul_f32 v[218:219], v[218:219], v[220:221]
	v_cndmask_b32_e64 v211, 0, 32, vcc
	v_rcp_f32_e32 v220, v220
	v_rcp_f32_e32 v221, v221
	v_ldexp_f32 v211, v217, v211
	v_log_f32_e32 v211, v211
	v_pk_mul_f32 v[238:239], v[106:107], v[238:239]
	v_rcp_f32_e32 v212, v134
	v_pk_mul_f32 v[220:221], v[238:239], v[220:221]
	v_cmp_lt_f32_e64 s[14:15], |v211|, s1
	v_cvt_pk_bf16_f32 v203, v220, v221
	v_mul_f32_e32 v220, 0x3f317217, v211
	v_fma_f32 v220, v211, s96, -v220
	v_fmac_f32_e32 v220, 0x3377d1cf, v211
	v_fmac_f32_e32 v220, 0x3f317217, v211
	v_cndmask_b32_e64 v211, v211, v220, s[14:15]
	v_cndmask_b32_e32 v220, 0, v223, vcc
	v_sub_f32_e32 v211, v211, v220
	v_mul_f32_e32 v134, 0xbfb8aa3b, v67
	v_exp_f32_e32 v134, v134
	v_pk_add_f32 v[216:217], v[216:217], 1.0 op_sel_hi:[1,0] neg_lo:[1,0] neg_hi:[1,0]
	v_cvt_pk_bf16_f32 v197, v214, v215
	s_waitcnt lgkmcnt(0)
	s_nop 1
	v_add_f32_dpp v205, v205, v205 row_shr:1 row_mask:0xf bank_mask:0xf
	v_add_f32_e32 v134, 1.0, v134
	v_rcp_f32_e32 v213, v134
	v_or_b32_e32 v134, s67, v162
	v_lshlrev_b64 v[134:135], 7, v[134:135]
	s_waitcnt lgkmcnt(0)
	s_nop 1
	v_add_f32_dpp v211, v211, v211 row_shr:1 row_mask:0xf bank_mask:0xf
	v_pk_fma_f32 v[212:213], v[212:213], v[130:131], v[128:129]
	v_lshl_add_u64 v[134:135], v[164:165], 0, v[134:135]
	v_cmp_gt_f32_e32 vcc, s47, v212
	v_cvt_pk_bf16_f32 v201, v218, v219
	s_waitcnt lgkmcnt(0)
	s_nop 1
	v_add_f32_dpp v205, v205, v205 row_shr:2 row_mask:0xf bank_mask:0xf
	s_waitcnt lgkmcnt(0)
	s_nop 1
	v_add_f32_dpp v211, v211, v211 row_shr:2 row_mask:0xf bank_mask:0xf
	s_waitcnt lgkmcnt(0)
	s_nop 1
	v_add_f32_dpp v205, v205, v205 row_shr:4 row_mask:0xf bank_mask:0xf
	s_waitcnt lgkmcnt(0)
	s_nop 1
	v_add_f32_dpp v211, v211, v211 row_shr:4 row_mask:0xf bank_mask:0xf
	s_waitcnt lgkmcnt(0)
	s_nop 1
	v_add_f32_dpp v205, v205, v205 row_shr:8 row_mask:0xf bank_mask:0xf
	s_waitcnt lgkmcnt(0)
	s_nop 1
	v_add_f32_dpp v211, v211, v211 row_shr:8 row_mask:0xf bank_mask:0xf
	s_nop 1
	v_mov_b32_dpp v220, v205 row_newbcast:15 row_mask:0xf bank_mask:0xf
	s_nop 1
	v_mov_b32_dpp v221, v211 row_newbcast:15 row_mask:0xf bank_mask:0xf
	v_add_f32_e32 v205, v205, v209
	v_mul_f32_e32 v205, 0xbfb8aa3b, v205
	s_waitcnt lgkmcnt(1)
	v_add_f32_e32 v240, v209, v220
	v_add_f32_e32 v209, v211, v207
	v_exp_f32_e32 v220, v205
	v_mul_f32_e32 v205, 0xbfb8aa3b, v209
	s_waitcnt lgkmcnt(0)
	v_add_f32_e32 v207, v207, v221
	v_exp_f32_e32 v221, v205
	v_mul_f32_e32 v205, 0xbfb8aa3b, v90
	v_exp_f32_e32 v205, v205
	v_pk_mul_f32 v[216:217], v[216:217], v[220:221]
	v_rcp_f32_e32 v220, v220
	v_add_f32_e32 v205, 1.0, v205
	v_rcp_f32_e32 v238, v205
	v_mul_f32_e32 v205, 0xbfb8aa3b, v91
	v_exp_f32_e32 v205, v205
	v_rcp_f32_e32 v221, v221
	v_cvt_pk_bf16_f32 v209, v216, v217
	v_add_f32_e32 v205, 1.0, v205
	v_rcp_f32_e32 v239, v205
	v_cndmask_b32_e64 v205, 0, 32, vcc
	v_ldexp_f32 v205, v212, v205
	v_log_f32_e32 v205, v205
	v_pk_mul_f32 v[238:239], v[90:91], v[238:239]
	v_cmp_lt_f32_e64 s[14:15], |v205|, s1
	v_pk_mul_f32 v[220:221], v[238:239], v[220:221]
	s_nop 0
	v_cvt_pk_bf16_f32 v211, v220, v221
	v_mul_f32_e32 v220, 0x3f317217, v205
	v_fma_f32 v220, v205, s96, -v220
	v_fmac_f32_e32 v220, 0x3377d1cf, v205
	v_fmac_f32_e32 v220, 0x3f317217, v205
	v_cndmask_b32_e64 v205, v205, v220, s[14:15]
	v_cndmask_b32_e32 v220, 0, v223, vcc
	v_cmp_gt_f32_e32 vcc, s47, v213
	v_sub_f32_e32 v205, v205, v220
	s_nop 0
	v_cndmask_b32_e64 v220, 0, 32, vcc
	v_ldexp_f32 v220, v213, v220
	v_log_f32_e32 v220, v220
	v_pk_add_f32 v[212:213], v[212:213], 1.0 op_sel_hi:[1,0] neg_lo:[1,0] neg_hi:[1,0]
	v_mul_f32_e32 v221, 0x3f317217, v220
	v_fma_f32 v221, v220, s96, -v221
	v_fmac_f32_e32 v221, 0x3377d1cf, v220
	v_fmac_f32_e32 v221, 0x3f317217, v220
	v_cmp_lt_f32_e64 s[14:15], |v220|, s1
	s_nop 1
	v_cndmask_b32_e64 v220, v220, v221, s[14:15]
	v_cndmask_b32_e32 v221, 0, v223, vcc
	v_sub_f32_e32 v220, v220, v221
	s_waitcnt lgkmcnt(0)
	s_nop 1
	v_add_f32_dpp v205, v205, v205 row_shr:1 row_mask:0xf bank_mask:0xf
	s_waitcnt lgkmcnt(0)
	s_nop 1
	v_add_f32_dpp v220, v220, v220 row_shr:1 row_mask:0xf bank_mask:0xf
	s_waitcnt lgkmcnt(0)
	s_nop 1
	v_add_f32_dpp v205, v205, v205 row_shr:2 row_mask:0xf bank_mask:0xf
	s_waitcnt lgkmcnt(0)
	s_nop 1
	v_add_f32_dpp v220, v220, v220 row_shr:2 row_mask:0xf bank_mask:0xf
	s_waitcnt lgkmcnt(0)
	s_nop 1
	v_add_f32_dpp v205, v205, v205 row_shr:4 row_mask:0xf bank_mask:0xf
	s_waitcnt lgkmcnt(0)
	s_nop 1
	v_add_f32_dpp v220, v220, v220 row_shr:4 row_mask:0xf bank_mask:0xf
	s_waitcnt lgkmcnt(0)
	s_nop 1
	v_add_f32_dpp v205, v205, v205 row_shr:8 row_mask:0xf bank_mask:0xf
	s_waitcnt lgkmcnt(0)
	s_nop 1
	v_add_f32_dpp v220, v220, v220 row_shr:8 row_mask:0xf bank_mask:0xf
	s_nop 1
	v_mov_b32_dpp v221, v205 row_newbcast:15 row_mask:0xf bank_mask:0xf
	s_nop 1
	v_mov_b32_dpp v238, v220 row_newbcast:15 row_mask:0xf bank_mask:0xf
	v_add_f32_e32 v239, v220, v207
	v_add_f32_e32 v205, v205, v240
	s_waitcnt lgkmcnt(1)
	v_add_f32_e32 v221, v240, v221
	v_mul_f32_e32 v220, 0x3fb8aa3b, v221
	s_waitcnt lgkmcnt(0)
	v_add_f32_e32 v207, v207, v238
	v_exp_f32_e32 v220, v220
	v_mul_f32_e32 v207, 0x3fb8aa3b, v207
	v_exp_f32_e32 v221, v207
	v_mul_f32_e32 v207, v214, v220
	v_cvt_pk_bf16_f32 v207, v207, s0
	global_store_short v[134:135], v207, off
	v_mul_f32_e32 v207, v215, v221
	v_cvt_pk_bf16_f32 v207, v207, s0
	global_store_short v[134:135], v207, off offset:128
	global_store_dwordx2 v[176:177], v[198:199], off offset:8
	global_store_dwordx2 v[178:179], v[196:197], off offset:8
	v_mul_f32_e32 v176, v218, v220
	v_cvt_pk_bf16_f32 v176, v176, s0
	global_store_short v[134:135], v176, off offset:32
	v_mul_f32_e32 v176, v219, v221
	v_cvt_pk_bf16_f32 v176, v176, s0
	global_store_short v[134:135], v176, off offset:160
	global_store_dwordx2 v[180:181], v[202:203], off offset:8
	global_store_dwordx2 v[182:183], v[200:201], off offset:8
	v_mul_f32_e32 v176, v216, v220
	v_cvt_pk_bf16_f32 v176, v176, s0
	global_store_short v[134:135], v176, off offset:64
	v_mul_f32_e32 v176, v217, v221
	v_cvt_pk_bf16_f32 v176, v176, s0
	global_store_short v[134:135], v176, off offset:192
	global_store_dwordx2 v[184:185], v[210:211], off offset:8
	global_store_dwordx2 v[186:187], v[208:209], off offset:8
	v_mul_f32_e32 v176, 0xbfb8aa3b, v205
	v_mul_f32_e32 v177, 0xbfb8aa3b, v239
	v_exp_f32_e32 v176, v176
	v_exp_f32_e32 v177, v177
	s_nop 0
	v_pk_mul_f32 v[178:179], v[212:213], v[176:177]
	s_nop 0
	v_mul_f32_e32 v180, v220, v178
	v_cvt_pk_bf16_f32 v180, v180, s0
	global_store_short v[134:135], v180, off offset:96
	v_mul_f32_e32 v180, v221, v179
	v_cvt_pk_bf16_f32 v180, v180, s0
	global_store_short v[134:135], v180, off offset:224
	v_mul_f32_e32 v135, 0xbfb8aa3b, v74
	v_exp_f32_e32 v135, v135
	v_rcp_f32_e32 v134, v176
	v_cvt_pk_bf16_f32 v205, v178, v179
	v_add_f32_e32 v135, 1.0, v135
	v_rcp_f32_e32 v176, v135
	v_rcp_f32_e32 v135, v177
	v_mul_f32_e32 v177, 0xbfb8aa3b, v75
	v_exp_f32_e32 v177, v177
	s_nop 0
	v_add_f32_e32 v177, 1.0, v177
	v_rcp_f32_e32 v177, v177
	s_nop 0
	v_pk_mul_f32 v[176:177], v[74:75], v[176:177]
	s_nop 0
	v_pk_mul_f32 v[134:135], v[176:177], v[134:135]
	s_nop 0
	v_cvt_pk_bf16_f32 v207, v134, v135
	global_store_dwordx2 v[188:189], v[206:207], off offset:8
	global_store_dwordx2 v[190:191], v[204:205], off offset:8
	s_and_saveexec_b64 s[14:15], s[4:5]
	s_cbranch_execz .LBB0_1954
	s_add_u32 s28, s33, s94
	s_addc_u32 s29, s0, s95
	s_lshl_b64 s[94:95], s[86:87], 2
	s_add_u32 s94, s28, s94
	s_addc_u32 s95, s29, s95
	global_store_dwordx2 v237, v[220:221], s[94:95] offset:24
.LBB0_1954:
	s_or_b64 exec, exec, s[14:15]
	v_mul_f32_e32 v134, 0xbfb8aa3b, v52
	v_exp_f32_e32 v134, v134
	s_add_u32 s14, s92, 2
	s_addc_u32 s15, s93, 0
	s_lshl_b64 s[92:93], s[14:15], 10
	v_add_f32_e32 v134, 1.0, v134
	v_rcp_f32_e32 v176, v134
	v_mul_f32_e32 v134, 0xbfb8aa3b, v53
	v_exp_f32_e32 v134, v134
	s_add_u32 s67, s92, s90
	s_addc_u32 s85, s93, s91
	s_lshl_b64 s[90:91], s[14:15], 12
	v_add_f32_e32 v134, 1.0, v134
	v_rcp_f32_e32 v177, v134
	v_mul_f32_e32 v134, 0xbfb8aa3b, v36
	v_exp_f32_e32 v134, v134
	v_mov_b32_e32 v135, s85
	v_pk_fma_f32 v[176:177], v[176:177], v[174:175], v[140:141]
	v_add_f32_e32 v134, 1.0, v134
	v_cmp_gt_f32_e32 vcc, s47, v176
	v_rcp_f32_e32 v184, v134
	v_mul_f32_e32 v134, 0xbfb8aa3b, v37
	v_cndmask_b32_e64 v178, 0, 32, vcc
	v_ldexp_f32 v178, v176, v178
	v_log_f32_e32 v178, v178
	v_exp_f32_e32 v134, v134
	v_mul_f32_e32 v179, 0x3f317217, v178
	v_fma_f32 v179, v178, s96, -v179
	v_fmac_f32_e32 v179, 0x3377d1cf, v178
	v_fmac_f32_e32 v179, 0x3f317217, v178
	v_cmp_lt_f32_e64 s[14:15], |v178|, s1
	v_add_f32_e32 v134, 1.0, v134
	v_rcp_f32_e32 v185, v134
	v_cndmask_b32_e64 v178, v178, v179, s[14:15]
	v_cndmask_b32_e32 v179, 0, v223, vcc
	v_cmp_gt_f32_e32 vcc, s47, v177
	v_sub_f32_e32 v178, v178, v179
	v_pk_fma_f32 v[184:185], v[184:185], v[174:175], v[140:141]
	v_cndmask_b32_e64 v179, 0, 32, vcc
	v_ldexp_f32 v179, v177, v179
	v_log_f32_e32 v179, v179
	v_mul_f32_e32 v134, 0xbfb8aa3b, v20
	v_exp_f32_e32 v134, v134
	v_pk_add_f32 v[176:177], v[176:177], 1.0 op_sel_hi:[1,0] neg_lo:[1,0] neg_hi:[1,0]
	v_mul_f32_e32 v186, 0x3f317217, v179
	v_fma_f32 v186, v179, s96, -v186
	v_fmac_f32_e32 v186, 0x3377d1cf, v179
	v_fmac_f32_e32 v186, 0x3f317217, v179
	v_cmp_lt_f32_e64 s[14:15], |v179|, s1
	v_add_f32_e32 v134, 1.0, v134
	v_rcp_f32_e32 v182, v134
	v_cndmask_b32_e64 v179, v179, v186, s[14:15]
	v_cndmask_b32_e32 v186, 0, v223, vcc
	v_cmp_gt_f32_e32 vcc, s47, v184
	v_sub_f32_e32 v179, v179, v186
	v_cndmask_b32_e64 v188, 0, 32, vcc
	v_ldexp_f32 v188, v184, v188
	v_log_f32_e32 v188, v188
	v_mul_f32_e32 v134, 0xbfb8aa3b, v21
	s_waitcnt lgkmcnt(0)
	s_nop 1
	v_add_f32_dpp v178, v178, v178 row_shr:1 row_mask:0xf bank_mask:0xf
	v_mul_f32_e32 v189, 0x3f317217, v188
	v_fma_f32 v189, v188, s96, -v189
	v_fmac_f32_e32 v189, 0x3377d1cf, v188
	v_fmac_f32_e32 v189, 0x3f317217, v188
	v_cmp_lt_f32_e64 s[14:15], |v188|, s1
	v_exp_f32_e32 v134, v134
	v_cndmask_b32_e64 v188, v188, v189, s[14:15]
	v_cndmask_b32_e32 v189, 0, v223, vcc
	v_cmp_gt_f32_e32 vcc, s47, v185
	v_sub_f32_e32 v188, v188, v189
	s_waitcnt lgkmcnt(0)
	v_cndmask_b32_e64 v189, 0, 32, vcc
	v_ldexp_f32 v189, v185, v189
	v_log_f32_e32 v189, v189
	s_nop 1
	v_add_f32_dpp v179, v179, v179 row_shr:1 row_mask:0xf bank_mask:0xf
	v_add_f32_e32 v134, 1.0, v134
	v_mul_f32_e32 v190, 0x3f317217, v189
	v_fma_f32 v190, v189, s96, -v190
	v_fmac_f32_e32 v190, 0x3377d1cf, v189
	v_fmac_f32_e32 v190, 0x3f317217, v189
	v_cmp_lt_f32_e64 s[14:15], |v189|, s1
	s_waitcnt lgkmcnt(0)
	s_nop 1
	v_add_f32_dpp v178, v178, v178 row_shr:2 row_mask:0xf bank_mask:0xf
	v_cndmask_b32_e64 v189, v189, v190, s[14:15]
	v_cndmask_b32_e32 v190, 0, v223, vcc
	v_sub_f32_e32 v189, v189, v190
	v_rcp_f32_e32 v183, v134
	v_pk_add_f32 v[184:185], v[184:185], 1.0 op_sel_hi:[1,0] neg_lo:[1,0] neg_hi:[1,0]
	v_mul_f32_e32 v134, 0xbfb8aa3b, v4
	s_waitcnt lgkmcnt(1)
	s_nop 1
	v_add_f32_dpp v188, v188, v188 row_shr:1 row_mask:0xf bank_mask:0xf
	s_waitcnt lgkmcnt(1)
	s_nop 1
	v_add_f32_dpp v179, v179, v179 row_shr:2 row_mask:0xf bank_mask:0xf
	v_pk_fma_f32 v[182:183], v[182:183], v[174:175], v[140:141]
	s_waitcnt lgkmcnt(1)
	s_nop 1
	v_add_f32_dpp v189, v189, v189 row_shr:1 row_mask:0xf bank_mask:0xf
	s_waitcnt lgkmcnt(1)
	s_nop 1
	v_add_f32_dpp v178, v178, v178 row_shr:4 row_mask:0xf bank_mask:0xf
	v_cmp_gt_f32_e32 vcc, s47, v182
	s_waitcnt lgkmcnt(1)
	s_nop 1
	v_add_f32_dpp v188, v188, v188 row_shr:2 row_mask:0xf bank_mask:0xf
	s_waitcnt lgkmcnt(1)
	s_nop 1
	v_add_f32_dpp v179, v179, v179 row_shr:4 row_mask:0xf bank_mask:0xf
	v_exp_f32_e32 v134, v134
	s_waitcnt lgkmcnt(1)
	s_nop 1
	v_add_f32_dpp v189, v189, v189 row_shr:2 row_mask:0xf bank_mask:0xf
	s_waitcnt lgkmcnt(1)
	s_nop 1
	v_add_f32_dpp v178, v178, v178 row_shr:8 row_mask:0xf bank_mask:0xf
	v_add_f32_e32 v134, 1.0, v134
	s_waitcnt lgkmcnt(1)
	s_nop 1
	v_add_f32_dpp v188, v188, v188 row_shr:4 row_mask:0xf bank_mask:0xf
	s_waitcnt lgkmcnt(1)
	s_nop 1
	v_add_f32_dpp v179, v179, v179 row_shr:8 row_mask:0xf bank_mask:0xf
	s_nop 1
	v_mov_b32_dpp v186, v178 row_newbcast:15 row_mask:0xf bank_mask:0xf
	s_nop 1
	v_mov_b32_dpp v187, v179 row_newbcast:15 row_mask:0xf bank_mask:0xf
	s_waitcnt lgkmcnt(2)
	s_nop 1
	v_add_f32_dpp v189, v189, v189 row_shr:4 row_mask:0xf bank_mask:0xf
	s_waitcnt lgkmcnt(2)
	v_add_f32_e32 v186, 0, v186
	s_waitcnt lgkmcnt(1)
	v_add_f32_e32 v187, 0, v187
	v_rcp_f32_e32 v180, v134
	v_mul_f32_e32 v134, 0xbfb8aa3b, v5
	s_waitcnt lgkmcnt(0)
	s_nop 1
	v_add_f32_dpp v188, v188, v188 row_shr:8 row_mask:0xf bank_mask:0xf
	v_exp_f32_e32 v134, v134
	v_add_f32_e32 v178, 0, v178
	v_add_f32_e32 v179, 0, v179
	v_mul_f32_e32 v178, 0xbfb8aa3b, v178
	s_waitcnt lgkmcnt(0)
	s_nop 1
	v_add_f32_dpp v189, v189, v189 row_shr:8 row_mask:0xf bank_mask:0xf
	s_nop 1
	v_mov_b32_dpp v190, v188 row_newbcast:15 row_mask:0xf bank_mask:0xf
	s_nop 1
	v_mov_b32_dpp v191, v189 row_newbcast:15 row_mask:0xf bank_mask:0xf
	v_add_f32_e32 v188, v188, v186
	v_add_f32_e32 v134, 1.0, v134
	v_rcp_f32_e32 v181, v134
	s_waitcnt lgkmcnt(1)
	v_add_f32_e32 v190, v186, v190
	v_add_f32_e32 v186, v189, v187
	s_waitcnt lgkmcnt(0)
	v_add_f32_e32 v191, v187, v191
	v_mul_f32_e32 v187, 0xbfb8aa3b, v188
	v_mul_f32_e32 v186, 0xbfb8aa3b, v186
	v_exp_f32_e32 v188, v187
	v_exp_f32_e32 v189, v186
	v_pk_fma_f32 v[140:141], v[180:181], v[174:175], v[140:141]
	v_mul_f32_e32 v179, 0xbfb8aa3b, v179
	v_exp_f32_e32 v178, v178
	v_pk_mul_f32 v[186:187], v[184:185], v[188:189]
	v_cndmask_b32_e64 v184, 0, 32, vcc
	v_ldexp_f32 v184, v182, v184
	v_log_f32_e32 v184, v184
	v_exp_f32_e32 v179, v179
	v_or_b32_e32 v134, s67, v154
	v_lshlrev_b64 v[134:135], 7, v[134:135]
	v_mul_f32_e32 v185, 0x3f317217, v184
	v_fma_f32 v185, v184, s96, -v185
	v_fmac_f32_e32 v185, 0x3377d1cf, v184
	v_fmac_f32_e32 v185, 0x3f317217, v184
	v_cmp_lt_f32_e64 s[14:15], |v184|, s1
	v_pk_mul_f32 v[176:177], v[176:177], v[178:179]
	v_lshl_add_u64 v[134:135], v[164:165], 0, v[134:135]
	v_cndmask_b32_e64 v184, v184, v185, s[14:15]
	v_cndmask_b32_e32 v185, 0, v223, vcc
	v_cmp_gt_f32_e32 vcc, s47, v183
	v_sub_f32_e32 v184, v184, v185
	s_nop 0
	v_cndmask_b32_e64 v185, 0, 32, vcc
	v_ldexp_f32 v185, v183, v185
	v_log_f32_e32 v185, v185
	v_pk_add_f32 v[182:183], v[182:183], 1.0 op_sel_hi:[1,0] neg_lo:[1,0] neg_hi:[1,0]
	v_mul_f32_e32 v196, 0x3f317217, v185
	v_fma_f32 v196, v185, s96, -v196
	v_fmac_f32_e32 v196, 0x3377d1cf, v185
	v_fmac_f32_e32 v196, 0x3f317217, v185
	v_cmp_lt_f32_e64 s[14:15], |v185|, s1
	s_nop 1
	v_cndmask_b32_e64 v185, v185, v196, s[14:15]
	v_cndmask_b32_e32 v196, 0, v223, vcc
	v_cmp_gt_f32_e32 vcc, s47, v140
	v_sub_f32_e32 v185, v185, v196
	v_cndmask_b32_e64 v174, 0, 32, vcc
	v_ldexp_f32 v174, v140, v174
	v_log_f32_e32 v174, v174
	s_waitcnt lgkmcnt(0)
	s_nop 1
	v_add_f32_dpp v184, v184, v184 row_shr:1 row_mask:0xf bank_mask:0xf
	v_mul_f32_e32 v175, 0x3f317217, v174
	v_fma_f32 v175, v174, s96, -v175
	v_fmac_f32_e32 v175, 0x3377d1cf, v174
	v_fmac_f32_e32 v175, 0x3f317217, v174
	v_cmp_lt_f32_e64 s[14:15], |v174|, s1
	s_waitcnt lgkmcnt(0)
	v_cndmask_b32_e64 v174, v174, v175, s[14:15]
	v_cndmask_b32_e32 v175, 0, v223, vcc
	v_cmp_gt_f32_e32 vcc, s47, v141
	v_sub_f32_e32 v174, v174, v175
	s_nop 1
	v_add_f32_dpp v185, v185, v185 row_shr:1 row_mask:0xf bank_mask:0xf
	v_cndmask_b32_e64 v175, 0, 32, vcc
	v_ldexp_f32 v175, v141, v175
	v_log_f32_e32 v175, v175
	v_pk_add_f32 v[140:141], v[140:141], 1.0 op_sel_hi:[1,0] neg_lo:[1,0] neg_hi:[1,0]
	v_mul_f32_e32 v180, 0x3f317217, v175
	v_fma_f32 v180, v175, s96, -v180
	v_fmac_f32_e32 v180, 0x3377d1cf, v175
	v_fmac_f32_e32 v180, 0x3f317217, v175
	v_cmp_lt_f32_e64 s[14:15], |v175|, s1
	s_waitcnt lgkmcnt(0)
	s_nop 1
	v_add_f32_dpp v184, v184, v184 row_shr:2 row_mask:0xf bank_mask:0xf
	v_cndmask_b32_e64 v175, v175, v180, s[14:15]
	v_cndmask_b32_e32 v180, 0, v223, vcc
	v_sub_f32_e32 v175, v175, v180
	s_waitcnt lgkmcnt(1)
	s_nop 1
	v_add_f32_dpp v174, v174, v174 row_shr:1 row_mask:0xf bank_mask:0xf
	s_waitcnt lgkmcnt(1)
	s_nop 1
	v_add_f32_dpp v185, v185, v185 row_shr:2 row_mask:0xf bank_mask:0xf
	s_waitcnt lgkmcnt(1)
	s_nop 1
	v_add_f32_dpp v175, v175, v175 row_shr:1 row_mask:0xf bank_mask:0xf
	s_waitcnt lgkmcnt(1)
	s_nop 1
	v_add_f32_dpp v184, v184, v184 row_shr:4 row_mask:0xf bank_mask:0xf
	s_waitcnt lgkmcnt(1)
	s_nop 1
	v_add_f32_dpp v174, v174, v174 row_shr:2 row_mask:0xf bank_mask:0xf
	s_waitcnt lgkmcnt(1)
	s_nop 1
	v_add_f32_dpp v185, v185, v185 row_shr:4 row_mask:0xf bank_mask:0xf
	s_waitcnt lgkmcnt(1)
	s_nop 1
	v_add_f32_dpp v175, v175, v175 row_shr:2 row_mask:0xf bank_mask:0xf
	s_waitcnt lgkmcnt(1)
	s_nop 1
	v_add_f32_dpp v184, v184, v184 row_shr:8 row_mask:0xf bank_mask:0xf
	s_waitcnt lgkmcnt(1)
	s_nop 1
	v_add_f32_dpp v174, v174, v174 row_shr:4 row_mask:0xf bank_mask:0xf
	s_waitcnt lgkmcnt(1)
	s_nop 1
	v_add_f32_dpp v185, v185, v185 row_shr:8 row_mask:0xf bank_mask:0xf
	s_nop 1
	v_mov_b32_dpp v196, v184 row_newbcast:15 row_mask:0xf bank_mask:0xf
	s_nop 1
	v_mov_b32_dpp v197, v185 row_newbcast:15 row_mask:0xf bank_mask:0xf
	s_waitcnt lgkmcnt(2)
	s_nop 1
	v_add_f32_dpp v175, v175, v175 row_shr:4 row_mask:0xf bank_mask:0xf
	v_add_f32_e32 v184, v184, v190
	s_waitcnt lgkmcnt(2)
	v_add_f32_e32 v198, v190, v196
	v_add_f32_e32 v185, v185, v191
	v_mul_f32_e32 v184, 0xbfb8aa3b, v184
	s_waitcnt lgkmcnt(0)
	s_nop 1
	v_add_f32_dpp v174, v174, v174 row_shr:8 row_mask:0xf bank_mask:0xf
	v_add_f32_e32 v199, v191, v197
	v_exp_f32_e32 v196, v184
	v_mul_f32_e32 v184, 0xbfb8aa3b, v185
	v_exp_f32_e32 v197, v184
	s_waitcnt lgkmcnt(0)
	s_nop 1
	v_add_f32_dpp v175, v175, v175 row_shr:8 row_mask:0xf bank_mask:0xf
	s_nop 1
	v_mov_b32_dpp v180, v174 row_newbcast:15 row_mask:0xf bank_mask:0xf
	s_nop 1
	v_mov_b32_dpp v181, v175 row_newbcast:15 row_mask:0xf bank_mask:0xf
	v_pk_mul_f32 v[190:191], v[182:183], v[196:197]
	v_add_f32_e32 v174, v174, v198
	v_add_f32_e32 v175, v175, v199
	s_waitcnt lgkmcnt(1)
	v_add_f32_e32 v180, v198, v180
	v_mul_f32_e32 v180, 0x3fb8aa3b, v180
	s_waitcnt lgkmcnt(0)
	v_add_f32_e32 v181, v199, v181
	v_exp_f32_e32 v180, v180
	v_mul_f32_e32 v181, 0x3fb8aa3b, v181
	v_exp_f32_e32 v181, v181
	v_mul_f32_e32 v174, 0xbfb8aa3b, v174
	v_mul_f32_e32 v182, v176, v180
	v_cvt_pk_bf16_f32 v182, v182, s0
	global_store_short v[134:135], v182, off
	v_mul_f32_e32 v182, v177, v181
	v_cvt_pk_bf16_f32 v182, v182, s0
	global_store_short v[134:135], v182, off offset:128
	v_mul_f32_e32 v182, v186, v180
	v_cvt_pk_bf16_f32 v182, v182, s0
	global_store_short v[134:135], v182, off offset:32
	v_mul_f32_e32 v182, v187, v181
	v_mul_f32_e32 v175, 0xbfb8aa3b, v175
	v_cvt_pk_bf16_f32 v182, v182, s0
	v_exp_f32_e32 v174, v174
	v_exp_f32_e32 v175, v175
	global_store_short v[134:135], v182, off offset:160
	v_mul_f32_e32 v182, v190, v180
	v_cvt_pk_bf16_f32 v182, v182, s0
	global_store_short v[134:135], v182, off offset:64
	v_mul_f32_e32 v182, v191, v181
	v_cvt_pk_bf16_f32 v182, v182, s0
	v_pk_mul_f32 v[140:141], v[140:141], v[174:175]
	global_store_short v[134:135], v182, off offset:192
	v_mul_f32_e32 v182, v180, v140
	v_cvt_pk_bf16_f32 v182, v182, s0
	global_store_short v[134:135], v182, off offset:96
	v_mul_f32_e32 v182, v181, v141
	v_cvt_pk_bf16_f32 v182, v182, s0
	global_store_short v[134:135], v182, off offset:224
	s_and_saveexec_b64 s[14:15], s[4:5]
	s_cbranch_execz .LBB0_1956
	s_add_u32 s28, s33, s90
	s_addc_u32 s29, s0, s91
	s_lshl_b64 s[92:93], s[86:87], 2
	s_add_u32 s92, s28, s92
	s_addc_u32 s93, s29, s93
	global_store_dwordx2 v237, v[180:181], s[92:93]
.LBB0_1956:
	s_or_b64 exec, exec, s[14:15]
	v_mul_f32_e32 v180, 0xbfb8aa3b, v60
	v_mul_f32_e32 v181, 0xbfb8aa3b, v61
	v_exp_f32_e32 v180, v180
	v_exp_f32_e32 v181, v181
	v_rcp_f32_e32 v178, v178
	v_rcp_f32_e32 v179, v179
	v_add_f32_e32 v180, 1.0, v180
	v_add_f32_e32 v181, 1.0, v181
	v_rcp_f32_e32 v180, v180
	v_rcp_f32_e32 v181, v181
	v_cvt_pk_bf16_f32 v182, v176, v177
	v_mul_f32_e32 v177, 0xbfb8aa3b, v44
	v_exp_f32_e32 v177, v177
	v_pk_mul_f32 v[180:181], v[60:61], v[180:181]
	v_rcp_f32_e32 v176, v188
	v_pk_mul_f32 v[178:179], v[180:181], v[178:179]
	v_add_f32_e32 v177, 1.0, v177
	v_cvt_pk_bf16_f32 v184, v178, v179
	v_mul_f32_e32 v179, 0xbfb8aa3b, v45
	v_exp_f32_e32 v179, v179
	v_rcp_f32_e32 v178, v177
	v_rcp_f32_e32 v177, v189
	v_rcp_f32_e32 v174, v174
	v_add_f32_e32 v179, 1.0, v179
	v_rcp_f32_e32 v179, v179
	v_rcp_f32_e32 v175, v175
	v_cvt_pk_bf16_f32 v198, v190, v191
	v_cvt_pk_bf16_f32 v190, v140, v141
	v_pk_mul_f32 v[178:179], v[44:45], v[178:179]
	v_mul_f32_e32 v140, 0xbfb8aa3b, v54
	v_pk_mul_f32 v[176:177], v[178:179], v[176:177]
	v_mul_f32_e32 v179, 0xbfb8aa3b, v29
	v_cvt_pk_bf16_f32 v188, v176, v177
	v_mul_f32_e32 v177, 0xbfb8aa3b, v28
	v_exp_f32_e32 v177, v177
	v_exp_f32_e32 v179, v179
	v_rcp_f32_e32 v176, v196
	v_mul_f32_e32 v141, 0xbfb8aa3b, v55
	v_add_f32_e32 v177, 1.0, v177
	v_add_f32_e32 v179, 1.0, v179
	v_rcp_f32_e32 v178, v177
	v_rcp_f32_e32 v179, v179
	v_rcp_f32_e32 v177, v197
	v_exp_f32_e32 v140, v140
	v_exp_f32_e32 v141, v141
	v_pk_mul_f32 v[178:179], v[28:29], v[178:179]
	v_lshlrev_b64 v[134:135], 10, v[172:173]
	v_pk_mul_f32 v[176:177], v[178:179], v[176:177]
	v_add_f32_e32 v140, 1.0, v140
	v_cvt_pk_bf16_f32 v200, v176, v177
	v_mul_f32_e32 v176, 0xbfb8aa3b, v12
	v_mul_f32_e32 v177, 0xbfb8aa3b, v13
	v_exp_f32_e32 v176, v176
	v_exp_f32_e32 v177, v177
	v_add_f32_e32 v141, 1.0, v141
	v_rcp_f32_e32 v140, v140
	v_add_f32_e32 v176, 1.0, v176
	v_add_f32_e32 v177, 1.0, v177
	v_rcp_f32_e32 v176, v176
	v_rcp_f32_e32 v177, v177
	v_rcp_f32_e32 v141, v141
	v_lshlrev_b64 v[204:205], 1, v[134:135]
	v_cvt_pk_bf16_f32 v186, v186, v187
	v_pk_mul_f32 v[176:177], v[12:13], v[176:177]
	v_pk_fma_f32 v[140:141], v[140:141], v[138:139], v[136:137]
	v_pk_mul_f32 v[174:175], v[176:177], v[174:175]
	v_mul_f32_e32 v176, 0xbfb8aa3b, v22
	v_exp_f32_e32 v176, v176
	v_mov_b32_e32 v177, s85
	v_cmp_gt_f32_e32 vcc, s47, v140
	v_cvt_pk_bf16_f32 v196, v174, v175
	v_add_f32_e32 v176, 1.0, v176
	v_rcp_f32_e32 v178, v176
	v_mul_f32_e32 v176, 0xbfb8aa3b, v23
	v_exp_f32_e32 v176, v176
	v_mul_f32_e32 v174, 0xbfb8aa3b, v38
	v_mul_f32_e32 v175, 0xbfb8aa3b, v39
	v_exp_f32_e32 v174, v174
	v_add_f32_e32 v176, 1.0, v176
	v_rcp_f32_e32 v179, v176
	v_mul_f32_e32 v176, 0xbfb8aa3b, v6
	v_exp_f32_e32 v176, v176
	v_exp_f32_e32 v175, v175
	v_add_f32_e32 v174, 1.0, v174
	v_rcp_f32_e32 v174, v174
	v_add_f32_e32 v176, 1.0, v176
	v_rcp_f32_e32 v206, v176
	v_mul_f32_e32 v176, 0xbfb8aa3b, v7
	v_exp_f32_e32 v176, v176
	v_add_f32_e32 v175, 1.0, v175
	v_rcp_f32_e32 v175, v175
	v_pk_fma_f32 v[178:179], v[178:179], v[138:139], v[136:137]
	v_add_f32_e32 v176, 1.0, v176
	v_rcp_f32_e32 v207, v176
	v_or_b32_e32 v176, s67, v158
	v_lshlrev_b64 v[176:177], 7, v[176:177]
	v_lshl_add_u64 v[202:203], v[164:165], 0, v[176:177]
	v_cndmask_b32_e64 v176, 0, 32, vcc
	v_ldexp_f32 v176, v140, v176
	v_log_f32_e32 v176, v176
	v_pk_fma_f32 v[174:175], v[174:175], v[138:139], v[136:137]
	v_pk_fma_f32 v[136:137], v[206:207], v[138:139], v[136:137]
	v_mul_f32_e32 v177, 0x3f317217, v176
	v_fma_f32 v177, v176, s96, -v177
	v_fmac_f32_e32 v177, 0x3377d1cf, v176
	v_fmac_f32_e32 v177, 0x3f317217, v176
	v_cmp_lt_f32_e64 s[14:15], |v176|, s1
	s_nop 1
	v_cndmask_b32_e64 v176, v176, v177, s[14:15]
	v_cndmask_b32_e32 v177, 0, v223, vcc
	v_cmp_gt_f32_e32 vcc, s47, v141
	v_sub_f32_e32 v176, v176, v177
	s_nop 0
	v_cndmask_b32_e64 v177, 0, 32, vcc
	v_ldexp_f32 v177, v141, v177
	v_log_f32_e32 v177, v177
	v_pk_add_f32 v[140:141], v[140:141], 1.0 op_sel_hi:[1,0] neg_lo:[1,0] neg_hi:[1,0]
	v_mul_f32_e32 v180, 0x3f317217, v177
	v_fma_f32 v180, v177, s96, -v180
	v_fmac_f32_e32 v180, 0x3377d1cf, v177
	v_fmac_f32_e32 v180, 0x3f317217, v177
	v_cmp_lt_f32_e64 s[14:15], |v177|, s1
	s_nop 1
	v_cndmask_b32_e64 v177, v177, v180, s[14:15]
	v_cndmask_b32_e32 v180, 0, v223, vcc
	v_sub_f32_e32 v177, v177, v180
	v_cmp_gt_f32_e32 vcc, s47, v174
	s_mov_b64 s[14:15], 0x40000
	s_waitcnt lgkmcnt(0)
	s_nop 1
	v_add_f32_dpp v176, v176, v176 row_shr:1 row_mask:0xf bank_mask:0xf
	s_waitcnt lgkmcnt(0)
	s_nop 1
	v_add_f32_dpp v177, v177, v177 row_shr:1 row_mask:0xf bank_mask:0xf
	s_waitcnt lgkmcnt(0)
	s_nop 1
	v_add_f32_dpp v176, v176, v176 row_shr:2 row_mask:0xf bank_mask:0xf
	s_waitcnt lgkmcnt(0)
	s_nop 1
	v_add_f32_dpp v177, v177, v177 row_shr:2 row_mask:0xf bank_mask:0xf
	s_waitcnt lgkmcnt(0)
	s_nop 1
	v_add_f32_dpp v176, v176, v176 row_shr:4 row_mask:0xf bank_mask:0xf
	s_waitcnt lgkmcnt(0)
	s_nop 1
	v_add_f32_dpp v177, v177, v177 row_shr:4 row_mask:0xf bank_mask:0xf
	s_waitcnt lgkmcnt(0)
	s_nop 1
	v_add_f32_dpp v176, v176, v176 row_shr:8 row_mask:0xf bank_mask:0xf
	s_waitcnt lgkmcnt(0)
	s_nop 1
	v_add_f32_dpp v177, v177, v177 row_shr:8 row_mask:0xf bank_mask:0xf
	s_nop 1
	v_mov_b32_dpp v180, v176 row_newbcast:15 row_mask:0xf bank_mask:0xf
	v_add_f32_e32 v176, 0, v176
	s_nop 1
	v_mov_b32_dpp v181, v177 row_newbcast:15 row_mask:0xf bank_mask:0xf
	v_add_f32_e32 v177, 0, v177
	v_mul_f32_e32 v176, 0xbfb8aa3b, v176
	v_mul_f32_e32 v177, 0xbfb8aa3b, v177
	v_exp_f32_e32 v176, v176
	v_exp_f32_e32 v177, v177
	s_waitcnt lgkmcnt(1)
	v_add_f32_e32 v180, 0, v180
	s_waitcnt lgkmcnt(0)
	v_add_f32_e32 v181, 0, v181
	v_pk_mul_f32 v[208:209], v[140:141], v[176:177]
	v_mul_f32_e32 v141, 0xbfb8aa3b, v62
	v_exp_f32_e32 v141, v141
	v_rcp_f32_e32 v140, v176
	v_cvt_pk_bf16_f32 v183, v208, v209
	v_add_f32_e32 v141, 1.0, v141
	v_rcp_f32_e32 v176, v141
	v_rcp_f32_e32 v141, v177
	v_mul_f32_e32 v177, 0xbfb8aa3b, v63
	v_exp_f32_e32 v177, v177
	s_nop 0
	v_add_f32_e32 v177, 1.0, v177
	v_rcp_f32_e32 v177, v177
	s_nop 0
	v_pk_mul_f32 v[176:177], v[62:63], v[176:177]
	s_nop 0
	v_pk_mul_f32 v[140:141], v[176:177], v[140:141]
	v_cndmask_b32_e64 v176, 0, 32, vcc
	v_ldexp_f32 v176, v174, v176
	v_log_f32_e32 v176, v176
	v_cvt_pk_bf16_f32 v185, v140, v141
	v_lshl_add_u64 v[140:141], v[204:205], 0, s[14:15]
	v_lshl_add_u64 v[134:135], s[44:45], 0, v[140:141]
	v_mul_f32_e32 v177, 0x3f317217, v176
	v_fma_f32 v177, v176, s96, -v177
	v_fmac_f32_e32 v177, 0x3377d1cf, v176
	v_fmac_f32_e32 v177, 0x3f317217, v176
	v_cmp_lt_f32_e64 s[14:15], |v176|, s1
	v_lshl_add_u64 v[140:141], s[48:49], 0, v[140:141]
	v_lshl_add_u64 v[134:135], v[134:135], 0, s[88:89]
	v_cndmask_b32_e64 v176, v176, v177, s[14:15]
	v_cndmask_b32_e32 v177, 0, v223, vcc
	v_cmp_gt_f32_e32 vcc, s47, v175
	v_sub_f32_e32 v176, v176, v177
	v_lshl_add_u64 v[140:141], v[140:141], 0, s[88:89]
	v_cndmask_b32_e64 v177, 0, 32, vcc
	v_ldexp_f32 v177, v175, v177
	v_log_f32_e32 v177, v177
	v_pk_add_f32 v[174:175], v[174:175], 1.0 op_sel_hi:[1,0] neg_lo:[1,0] neg_hi:[1,0]
	v_lshl_add_u64 v[134:135], v[134:135], 0, v[152:153]
	v_lshl_add_u64 v[140:141], v[140:141], 0, v[152:153]
	v_mul_f32_e32 v187, 0x3f317217, v177
	v_fma_f32 v187, v177, s96, -v187
	v_fmac_f32_e32 v187, 0x3377d1cf, v177
	v_fmac_f32_e32 v187, 0x3f317217, v177
	v_cmp_lt_f32_e64 s[14:15], |v177|, s1
	s_nop 1
	v_cndmask_b32_e64 v177, v177, v187, s[14:15]
	v_cndmask_b32_e32 v187, 0, v223, vcc
	v_sub_f32_e32 v177, v177, v187
	v_cmp_gt_f32_e32 vcc, s47, v178
	s_mov_b64 s[14:15], 0x48000
	s_waitcnt lgkmcnt(0)
	s_nop 1
	v_add_f32_dpp v176, v176, v176 row_shr:1 row_mask:0xf bank_mask:0xf
	v_cndmask_b32_e64 v191, 0, 32, vcc
	v_ldexp_f32 v191, v178, v191
	v_log_f32_e32 v191, v191
	s_waitcnt lgkmcnt(0)
	s_nop 1
	v_add_f32_dpp v177, v177, v177 row_shr:1 row_mask:0xf bank_mask:0xf
	v_mul_f32_e32 v197, 0x3f317217, v191
	v_fma_f32 v197, v191, s96, -v197
	v_fmac_f32_e32 v197, 0x3377d1cf, v191
	v_fmac_f32_e32 v197, 0x3f317217, v191
	s_waitcnt lgkmcnt(0)
	s_nop 1
	v_add_f32_dpp v176, v176, v176 row_shr:2 row_mask:0xf bank_mask:0xf
	s_waitcnt lgkmcnt(0)
	s_nop 1
	v_add_f32_dpp v177, v177, v177 row_shr:2 row_mask:0xf bank_mask:0xf
	s_waitcnt lgkmcnt(0)
	s_nop 1
	v_add_f32_dpp v176, v176, v176 row_shr:4 row_mask:0xf bank_mask:0xf
	s_waitcnt lgkmcnt(0)
	s_nop 1
	v_add_f32_dpp v177, v177, v177 row_shr:4 row_mask:0xf bank_mask:0xf
	s_waitcnt lgkmcnt(0)
	s_nop 1
	v_add_f32_dpp v176, v176, v176 row_shr:8 row_mask:0xf bank_mask:0xf
	s_waitcnt lgkmcnt(0)
	s_nop 1
	v_add_f32_dpp v177, v177, v177 row_shr:8 row_mask:0xf bank_mask:0xf
	s_nop 1
	v_mov_b32_dpp v187, v176 row_newbcast:15 row_mask:0xf bank_mask:0xf
	s_nop 1
	v_mov_b32_dpp v189, v177 row_newbcast:15 row_mask:0xf bank_mask:0xf
	v_add_f32_e32 v176, v176, v180
	v_add_f32_e32 v177, v177, v181
	v_mul_f32_e32 v176, 0xbfb8aa3b, v176
	v_mul_f32_e32 v177, 0xbfb8aa3b, v177
	v_exp_f32_e32 v176, v176
	v_exp_f32_e32 v177, v177
	s_waitcnt lgkmcnt(1)
	v_add_f32_e32 v180, v180, v187
	s_waitcnt lgkmcnt(0)
	v_add_f32_e32 v181, v181, v189
	v_pk_mul_f32 v[210:211], v[174:175], v[176:177]
	v_mul_f32_e32 v175, 0xbfb8aa3b, v46
	v_exp_f32_e32 v175, v175
	v_rcp_f32_e32 v174, v176
	v_cvt_pk_bf16_f32 v187, v210, v211
	v_add_f32_e32 v175, 1.0, v175
	v_rcp_f32_e32 v176, v175
	v_rcp_f32_e32 v175, v177
	v_mul_f32_e32 v177, 0xbfb8aa3b, v47
	v_exp_f32_e32 v177, v177
	s_nop 0
	v_add_f32_e32 v177, 1.0, v177
	v_rcp_f32_e32 v177, v177
	s_nop 0
	v_pk_mul_f32 v[176:177], v[46:47], v[176:177]
	s_nop 0
	v_pk_mul_f32 v[174:175], v[176:177], v[174:175]
	v_lshl_add_u64 v[176:177], v[204:205], 0, s[14:15]
	v_cmp_lt_f32_e64 s[14:15], |v191|, s1
	v_cvt_pk_bf16_f32 v189, v174, v175
	v_lshl_add_u64 v[174:175], s[44:45], 0, v[176:177]
	v_cndmask_b32_e64 v191, v191, v197, s[14:15]
	v_cndmask_b32_e32 v197, 0, v223, vcc
	v_cmp_gt_f32_e32 vcc, s47, v179
	v_sub_f32_e32 v191, v191, v197
	v_lshl_add_u64 v[176:177], s[48:49], 0, v[176:177]
	v_cndmask_b32_e64 v197, 0, 32, vcc
	v_ldexp_f32 v197, v179, v197
	v_log_f32_e32 v197, v197
	v_pk_add_f32 v[178:179], v[178:179], 1.0 op_sel_hi:[1,0] neg_lo:[1,0] neg_hi:[1,0]
	v_lshl_add_u64 v[174:175], v[174:175], 0, s[88:89]
	v_lshl_add_u64 v[176:177], v[176:177], 0, s[88:89]
	v_mul_f32_e32 v199, 0x3f317217, v197
	v_fma_f32 v199, v197, s96, -v199
	v_fmac_f32_e32 v199, 0x3377d1cf, v197
	v_fmac_f32_e32 v199, 0x3f317217, v197
	v_cmp_lt_f32_e64 s[14:15], |v197|, s1
	v_lshl_add_u64 v[174:175], v[174:175], 0, v[152:153]
	v_lshl_add_u64 v[176:177], v[176:177], 0, v[152:153]
	v_cndmask_b32_e64 v197, v197, v199, s[14:15]
	v_cndmask_b32_e32 v199, 0, v223, vcc
	v_sub_f32_e32 v197, v197, v199
	v_cmp_gt_f32_e32 vcc, s47, v136
	s_mov_b64 s[14:15], 0x50000
	s_waitcnt lgkmcnt(0)
	s_nop 1
	v_add_f32_dpp v191, v191, v191 row_shr:1 row_mask:0xf bank_mask:0xf
	v_cndmask_b32_e64 v138, 0, 32, vcc
	v_ldexp_f32 v138, v136, v138
	v_log_f32_e32 v138, v138
	s_waitcnt lgkmcnt(0)
	s_nop 1
	v_add_f32_dpp v197, v197, v197 row_shr:1 row_mask:0xf bank_mask:0xf
	v_mul_f32_e32 v139, 0x3f317217, v138
	v_fma_f32 v139, v138, s96, -v139
	v_fmac_f32_e32 v139, 0x3377d1cf, v138
	v_fmac_f32_e32 v139, 0x3f317217, v138
	s_waitcnt lgkmcnt(0)
	s_nop 1
	v_add_f32_dpp v191, v191, v191 row_shr:2 row_mask:0xf bank_mask:0xf
	s_waitcnt lgkmcnt(0)
	s_nop 1
	v_add_f32_dpp v197, v197, v197 row_shr:2 row_mask:0xf bank_mask:0xf
	s_waitcnt lgkmcnt(0)
	s_nop 1
	v_add_f32_dpp v191, v191, v191 row_shr:4 row_mask:0xf bank_mask:0xf
	s_waitcnt lgkmcnt(0)
	s_nop 1
	v_add_f32_dpp v197, v197, v197 row_shr:4 row_mask:0xf bank_mask:0xf
	s_waitcnt lgkmcnt(0)
	s_nop 1
	v_add_f32_dpp v191, v191, v191 row_shr:8 row_mask:0xf bank_mask:0xf
	s_waitcnt lgkmcnt(0)
	s_nop 1
	v_add_f32_dpp v197, v197, v197 row_shr:8 row_mask:0xf bank_mask:0xf
	s_nop 1
	v_mov_b32_dpp v199, v191 row_newbcast:15 row_mask:0xf bank_mask:0xf
	s_nop 1
	v_mov_b32_dpp v201, v197 row_newbcast:15 row_mask:0xf bank_mask:0xf
	v_add_f32_e32 v191, v191, v180
	v_add_f32_e32 v197, v197, v181
	s_waitcnt lgkmcnt(1)
	v_add_f32_e32 v214, v180, v199
	s_waitcnt lgkmcnt(0)
	v_add_f32_e32 v215, v181, v201
	v_mul_f32_e32 v180, 0xbfb8aa3b, v191
	v_mul_f32_e32 v181, 0xbfb8aa3b, v197
	v_exp_f32_e32 v180, v180
	v_exp_f32_e32 v181, v181
	s_nop 0
	v_pk_mul_f32 v[212:213], v[178:179], v[180:181]
	v_mul_f32_e32 v179, 0xbfb8aa3b, v30
	v_exp_f32_e32 v179, v179
	v_rcp_f32_e32 v178, v180
	v_cvt_pk_bf16_f32 v199, v212, v213
	v_add_f32_e32 v179, 1.0, v179
	v_rcp_f32_e32 v180, v179
	v_rcp_f32_e32 v179, v181
	v_mul_f32_e32 v181, 0xbfb8aa3b, v31
	v_exp_f32_e32 v181, v181
	s_nop 0
	v_add_f32_e32 v181, 1.0, v181
	v_rcp_f32_e32 v181, v181
	s_nop 0
	v_pk_mul_f32 v[180:181], v[30:31], v[180:181]
	s_nop 0
	v_pk_mul_f32 v[178:179], v[180:181], v[178:179]
	v_lshl_add_u64 v[180:181], v[204:205], 0, s[14:15]
	v_cmp_lt_f32_e64 s[14:15], |v138|, s1
	v_cvt_pk_bf16_f32 v201, v178, v179
	v_lshl_add_u64 v[178:179], s[44:45], 0, v[180:181]
	v_cndmask_b32_e64 v138, v138, v139, s[14:15]
	v_cndmask_b32_e32 v139, 0, v223, vcc
	v_cmp_gt_f32_e32 vcc, s47, v137
	v_sub_f32_e32 v138, v138, v139
	v_lshl_add_u64 v[180:181], s[48:49], 0, v[180:181]
	v_cndmask_b32_e64 v139, 0, 32, vcc
	v_ldexp_f32 v139, v137, v139
	v_log_f32_e32 v139, v139
	v_pk_add_f32 v[136:137], v[136:137], 1.0 op_sel_hi:[1,0] neg_lo:[1,0] neg_hi:[1,0]
	v_lshl_add_u64 v[178:179], v[178:179], 0, s[88:89]
	v_lshl_add_u64 v[180:181], v[180:181], 0, s[88:89]
	v_mul_f32_e32 v191, 0x3f317217, v139
	v_fma_f32 v191, v139, s96, -v191
	v_fmac_f32_e32 v191, 0x3377d1cf, v139
	v_fmac_f32_e32 v191, 0x3f317217, v139
	v_cmp_lt_f32_e64 s[14:15], |v139|, s1
	v_lshl_add_u64 v[178:179], v[178:179], 0, v[152:153]
	v_lshl_add_u64 v[180:181], v[180:181], 0, v[152:153]
	v_cndmask_b32_e64 v139, v139, v191, s[14:15]
	v_cndmask_b32_e32 v191, 0, v223, vcc
	v_sub_f32_e32 v139, v139, v191
	s_mov_b64 s[14:15], 0x58000
	s_waitcnt lgkmcnt(0)
	s_nop 1
	v_add_f32_dpp v138, v138, v138 row_shr:1 row_mask:0xf bank_mask:0xf
	s_waitcnt lgkmcnt(0)
	s_nop 1
	v_add_f32_dpp v139, v139, v139 row_shr:1 row_mask:0xf bank_mask:0xf
	s_waitcnt lgkmcnt(0)
	s_nop 1
	v_add_f32_dpp v138, v138, v138 row_shr:2 row_mask:0xf bank_mask:0xf
	s_waitcnt lgkmcnt(0)
	s_nop 1
	v_add_f32_dpp v139, v139, v139 row_shr:2 row_mask:0xf bank_mask:0xf
	s_waitcnt lgkmcnt(0)
	s_nop 1
	v_add_f32_dpp v138, v138, v138 row_shr:4 row_mask:0xf bank_mask:0xf
	s_waitcnt lgkmcnt(0)
	s_nop 1
	v_add_f32_dpp v139, v139, v139 row_shr:4 row_mask:0xf bank_mask:0xf
	s_waitcnt lgkmcnt(0)
	s_nop 1
	v_add_f32_dpp v138, v138, v138 row_shr:8 row_mask:0xf bank_mask:0xf
	s_waitcnt lgkmcnt(0)
	s_nop 1
	v_add_f32_dpp v139, v139, v139 row_shr:8 row_mask:0xf bank_mask:0xf
	s_nop 1
	v_mov_b32_dpp v191, v138 row_newbcast:15 row_mask:0xf bank_mask:0xf
	s_nop 1
	v_mov_b32_dpp v197, v139 row_newbcast:15 row_mask:0xf bank_mask:0xf
	v_add_f32_e32 v138, v138, v214
	v_add_f32_e32 v139, v139, v215
	v_mul_f32_e32 v138, 0xbfb8aa3b, v138
	s_waitcnt lgkmcnt(1)
	v_add_f32_e32 v191, v214, v191
	v_mul_f32_e32 v191, 0x3fb8aa3b, v191
	s_waitcnt lgkmcnt(0)
	v_add_f32_e32 v197, v215, v197
	v_exp_f32_e32 v206, v191
	v_mul_f32_e32 v191, 0x3fb8aa3b, v197
	v_exp_f32_e32 v207, v191
	v_mul_f32_e32 v139, 0xbfb8aa3b, v139
	v_mul_f32_e32 v191, v208, v206
	v_cvt_pk_bf16_f32 v191, v191, s0
	global_store_short v[202:203], v191, off
	v_mul_f32_e32 v191, v209, v207
	v_cvt_pk_bf16_f32 v191, v191, s0
	global_store_short v[202:203], v191, off offset:128
	global_store_dwordx2 v[134:135], v[184:185], off
	global_store_dwordx2 v[140:141], v[182:183], off
	v_mul_f32_e32 v182, v210, v206
	v_cvt_pk_bf16_f32 v182, v182, s0
	global_store_short v[202:203], v182, off offset:32
	v_mul_f32_e32 v182, v211, v207
	v_cvt_pk_bf16_f32 v182, v182, s0
	v_exp_f32_e32 v138, v138
	v_exp_f32_e32 v139, v139
	global_store_short v[202:203], v182, off offset:160
	global_store_dwordx2 v[174:175], v[188:189], off
	global_store_dwordx2 v[176:177], v[186:187], off
	v_mul_f32_e32 v182, v212, v206
	v_cvt_pk_bf16_f32 v182, v182, s0
	global_store_short v[202:203], v182, off offset:64
	v_mul_f32_e32 v182, v213, v207
	v_cvt_pk_bf16_f32 v182, v182, s0
	v_pk_mul_f32 v[136:137], v[136:137], v[138:139]
	global_store_short v[202:203], v182, off offset:192
	global_store_dwordx2 v[178:179], v[200:201], off
	global_store_dwordx2 v[180:181], v[198:199], off
	v_mul_f32_e32 v182, v206, v136
	v_cvt_pk_bf16_f32 v182, v182, s0
	global_store_short v[202:203], v182, off offset:96
	v_mul_f32_e32 v182, v207, v137
	v_cvt_pk_bf16_f32 v182, v182, s0
	global_store_short v[202:203], v182, off offset:224
	v_mul_f32_e32 v182, 0xbfb8aa3b, v14
	v_mul_f32_e32 v183, 0xbfb8aa3b, v15
	v_exp_f32_e32 v182, v182
	v_exp_f32_e32 v183, v183
	v_rcp_f32_e32 v138, v138
	v_rcp_f32_e32 v139, v139
	v_add_f32_e32 v182, 1.0, v182
	v_add_f32_e32 v183, 1.0, v183
	v_rcp_f32_e32 v182, v182
	v_rcp_f32_e32 v183, v183
	v_cvt_pk_bf16_f32 v191, v136, v137
	v_pk_mul_f32 v[182:183], v[14:15], v[182:183]
	s_nop 0
	v_pk_mul_f32 v[138:139], v[182:183], v[138:139]
	s_nop 0
	v_cvt_pk_bf16_f32 v197, v138, v139
	v_lshl_add_u64 v[138:139], v[204:205], 0, s[14:15]
	v_lshl_add_u64 v[136:137], s[44:45], 0, v[138:139]
	v_lshl_add_u64 v[138:139], s[48:49], 0, v[138:139]
	v_lshl_add_u64 v[136:137], v[136:137], 0, s[88:89]
	v_lshl_add_u64 v[138:139], v[138:139], 0, s[88:89]
	v_lshl_add_u64 v[136:137], v[136:137], 0, v[152:153]
	v_lshl_add_u64 v[138:139], v[138:139], 0, v[152:153]
	global_store_dwordx2 v[136:137], v[196:197], off
	global_store_dwordx2 v[138:139], v[190:191], off
	s_and_saveexec_b64 s[14:15], s[4:5]
	s_cbranch_execz .LBB0_1958
	s_add_u32 s28, s33, s90
	s_addc_u32 s29, s0, s91
	s_lshl_b64 s[88:89], s[86:87], 2
	s_add_u32 s88, s28, s88
	s_addc_u32 s89, s29, s89
	global_store_dwordx2 v237, v[206:207], s[88:89] offset:8
.LBB0_1958:
	s_or_b64 exec, exec, s[14:15]
	v_mul_f32_e32 v152, 0xbfb8aa3b, v48
	v_exp_f32_e32 v152, v152
	v_mov_b32_e32 v183, s85
	v_or_b32_e32 v182, s67, v160
	v_lshlrev_b64 v[182:183], 7, v[182:183]
	v_add_f32_e32 v152, 1.0, v152
	v_rcp_f32_e32 v184, v152
	v_mul_f32_e32 v152, 0xbfb8aa3b, v49
	v_exp_f32_e32 v152, v152
	v_lshl_add_u64 v[182:183], v[164:165], 0, v[182:183]
	v_add_f32_e32 v152, 1.0, v152
	v_rcp_f32_e32 v185, v152
	v_mul_f32_e32 v152, 0xbfb8aa3b, v32
	v_exp_f32_e32 v152, v152
	v_pk_fma_f32 v[184:185], v[184:185], v[142:143], v[132:133]
	s_nop 0
	v_cmp_gt_f32_e32 vcc, s47, v184
	v_add_f32_e32 v152, 1.0, v152
	v_rcp_f32_e32 v190, v152
	v_mul_f32_e32 v152, 0xbfb8aa3b, v33
	v_exp_f32_e32 v152, v152
	s_nop 0
	v_add_f32_e32 v152, 1.0, v152
	v_rcp_f32_e32 v191, v152
	v_mul_f32_e32 v152, 0xbfb8aa3b, v16
	v_exp_f32_e32 v152, v152
	v_pk_fma_f32 v[190:191], v[190:191], v[142:143], v[132:133]
	v_add_f32_e32 v152, 1.0, v152
	v_rcp_f32_e32 v198, v152
	v_mul_f32_e32 v152, 0xbfb8aa3b, v17
	v_exp_f32_e32 v152, v152
	s_nop 0
	v_add_f32_e32 v152, 1.0, v152
	v_rcp_f32_e32 v199, v152
	v_mul_f32_e32 v152, 0xbfb8aa3b, v0
	v_exp_f32_e32 v152, v152
	v_pk_fma_f32 v[198:199], v[198:199], v[142:143], v[132:133]
	v_add_f32_e32 v152, 1.0, v152
	v_rcp_f32_e32 v188, v152
	v_mul_f32_e32 v152, 0xbfb8aa3b, v1
	v_exp_f32_e32 v152, v152
	s_nop 0
	v_add_f32_e32 v152, 1.0, v152
	v_rcp_f32_e32 v189, v152
	v_cndmask_b32_e64 v152, 0, 32, vcc
	v_ldexp_f32 v152, v184, v152
	v_log_f32_e32 v152, v152
	v_pk_fma_f32 v[132:133], v[188:189], v[142:143], v[132:133]
	v_mul_f32_e32 v186, 0x3f317217, v152
	v_fma_f32 v186, v152, s96, -v186
	v_fmac_f32_e32 v186, 0x3377d1cf, v152
	v_fmac_f32_e32 v186, 0x3f317217, v152
	v_cmp_lt_f32_e64 s[14:15], |v152|, s1
	s_nop 1
	v_cndmask_b32_e64 v152, v152, v186, s[14:15]
	v_cndmask_b32_e32 v186, 0, v223, vcc
	v_cmp_gt_f32_e32 vcc, s47, v185
	v_sub_f32_e32 v152, v152, v186
	s_nop 0
	v_cndmask_b32_e64 v186, 0, 32, vcc
	v_ldexp_f32 v186, v185, v186
	v_log_f32_e32 v186, v186
	v_pk_add_f32 v[184:185], v[184:185], 1.0 op_sel_hi:[1,0] neg_lo:[1,0] neg_hi:[1,0]
	v_mul_f32_e32 v187, 0x3f317217, v186
	v_fma_f32 v187, v186, s96, -v187
	v_fmac_f32_e32 v187, 0x3377d1cf, v186
	v_fmac_f32_e32 v187, 0x3f317217, v186
	v_cmp_lt_f32_e64 s[14:15], |v186|, s1
	s_nop 1
	v_cndmask_b32_e64 v186, v186, v187, s[14:15]
	v_cndmask_b32_e32 v187, 0, v223, vcc
	v_sub_f32_e32 v186, v186, v187
	v_cmp_gt_f32_e32 vcc, s47, v190
	s_waitcnt lgkmcnt(0)
	s_nop 1
	v_add_f32_dpp v152, v152, v152 row_shr:1 row_mask:0xf bank_mask:0xf
	s_waitcnt lgkmcnt(0)
	s_nop 1
	v_add_f32_dpp v186, v186, v186 row_shr:1 row_mask:0xf bank_mask:0xf
	s_waitcnt lgkmcnt(0)
	s_nop 1
	v_add_f32_dpp v152, v152, v152 row_shr:2 row_mask:0xf bank_mask:0xf
	s_waitcnt lgkmcnt(0)
	s_nop 1
	v_add_f32_dpp v186, v186, v186 row_shr:2 row_mask:0xf bank_mask:0xf
	s_waitcnt lgkmcnt(0)
	s_nop 1
	v_add_f32_dpp v152, v152, v152 row_shr:4 row_mask:0xf bank_mask:0xf
	s_waitcnt lgkmcnt(0)
	s_nop 1
	v_add_f32_dpp v186, v186, v186 row_shr:4 row_mask:0xf bank_mask:0xf
	s_waitcnt lgkmcnt(0)
	s_nop 1
	v_add_f32_dpp v152, v152, v152 row_shr:8 row_mask:0xf bank_mask:0xf
	s_waitcnt lgkmcnt(0)
	s_nop 1
	v_add_f32_dpp v186, v186, v186 row_shr:8 row_mask:0xf bank_mask:0xf
	s_nop 1
	v_mov_b32_dpp v187, v152 row_newbcast:15 row_mask:0xf bank_mask:0xf
	v_add_f32_e32 v152, 0, v152
	v_add_f32_e32 v197, 0, v186
	v_mul_f32_e32 v152, 0xbfb8aa3b, v152
	s_waitcnt lgkmcnt(0)
	v_add_f32_e32 v196, 0, v187
	s_nop 1
	v_mov_b32_dpp v187, v186 row_newbcast:15 row_mask:0xf bank_mask:0xf
	v_exp_f32_e32 v186, v152
	v_mul_f32_e32 v152, 0xbfb8aa3b, v197
	s_waitcnt lgkmcnt(0)
	v_add_f32_e32 v200, 0, v187
	v_exp_f32_e32 v187, v152
	v_cndmask_b32_e64 v152, 0, 32, vcc
	v_ldexp_f32 v152, v190, v152
	v_log_f32_e32 v152, v152
	v_pk_mul_f32 v[184:185], v[184:185], v[186:187]
	v_mul_f32_e32 v197, 0x3f317217, v152
	v_fma_f32 v197, v152, s96, -v197
	v_fmac_f32_e32 v197, 0x3377d1cf, v152
	v_fmac_f32_e32 v197, 0x3f317217, v152
	v_cmp_lt_f32_e64 s[14:15], |v152|, s1
	s_nop 1
	v_cndmask_b32_e64 v152, v152, v197, s[14:15]
	v_cndmask_b32_e32 v197, 0, v223, vcc
	v_cmp_gt_f32_e32 vcc, s47, v191
	v_sub_f32_e32 v152, v152, v197
	s_nop 0
	v_cndmask_b32_e64 v197, 0, 32, vcc
	v_ldexp_f32 v197, v191, v197
	v_log_f32_e32 v197, v197
	v_pk_add_f32 v[190:191], v[190:191], 1.0 op_sel_hi:[1,0] neg_lo:[1,0] neg_hi:[1,0]
	v_mul_f32_e32 v201, 0x3f317217, v197
	v_fma_f32 v201, v197, s96, -v201
	v_fmac_f32_e32 v201, 0x3377d1cf, v197
	v_fmac_f32_e32 v201, 0x3f317217, v197
	v_cmp_lt_f32_e64 s[14:15], |v197|, s1
	s_nop 1
	v_cndmask_b32_e64 v197, v197, v201, s[14:15]
	v_cndmask_b32_e32 v201, 0, v223, vcc
	v_sub_f32_e32 v197, v197, v201
	v_cmp_gt_f32_e32 vcc, s47, v198
	s_waitcnt lgkmcnt(0)
	s_nop 1
	v_add_f32_dpp v152, v152, v152 row_shr:1 row_mask:0xf bank_mask:0xf
	s_waitcnt lgkmcnt(0)
	s_nop 1
	v_add_f32_dpp v197, v197, v197 row_shr:1 row_mask:0xf bank_mask:0xf
	s_waitcnt lgkmcnt(0)
	s_nop 1
	v_add_f32_dpp v152, v152, v152 row_shr:2 row_mask:0xf bank_mask:0xf
	s_waitcnt lgkmcnt(0)
	s_nop 1
	v_add_f32_dpp v197, v197, v197 row_shr:2 row_mask:0xf bank_mask:0xf
	s_waitcnt lgkmcnt(0)
	s_nop 1
	v_add_f32_dpp v152, v152, v152 row_shr:4 row_mask:0xf bank_mask:0xf
	s_waitcnt lgkmcnt(0)
	s_nop 1
	v_add_f32_dpp v197, v197, v197 row_shr:4 row_mask:0xf bank_mask:0xf
	s_waitcnt lgkmcnt(0)
	s_nop 1
	v_add_f32_dpp v152, v152, v152 row_shr:8 row_mask:0xf bank_mask:0xf
	s_waitcnt lgkmcnt(0)
	s_nop 1
	v_add_f32_dpp v197, v197, v197 row_shr:8 row_mask:0xf bank_mask:0xf
	s_nop 1
	v_mov_b32_dpp v201, v152 row_newbcast:15 row_mask:0xf bank_mask:0xf
	v_add_f32_e32 v152, v152, v196
	s_nop 1
	v_mov_b32_dpp v202, v197 row_newbcast:15 row_mask:0xf bank_mask:0xf
	v_add_f32_e32 v197, v197, v200
	v_mul_f32_e32 v152, 0xbfb8aa3b, v152
	s_waitcnt lgkmcnt(1)
	v_add_f32_e32 v201, v196, v201
	v_exp_f32_e32 v196, v152
	v_mul_f32_e32 v152, 0xbfb8aa3b, v197
	v_exp_f32_e32 v197, v152
	v_cndmask_b32_e64 v152, 0, 32, vcc
	v_ldexp_f32 v152, v198, v152
	v_log_f32_e32 v152, v152
	s_waitcnt lgkmcnt(0)
	v_add_f32_e32 v200, v200, v202
	v_pk_mul_f32 v[190:191], v[190:191], v[196:197]
	v_mul_f32_e32 v202, 0x3f317217, v152
	v_fma_f32 v202, v152, s96, -v202
	v_fmac_f32_e32 v202, 0x3377d1cf, v152
	v_fmac_f32_e32 v202, 0x3f317217, v152
	v_cmp_lt_f32_e64 s[14:15], |v152|, s1
	s_nop 1
	v_cndmask_b32_e64 v152, v152, v202, s[14:15]
	v_cndmask_b32_e32 v202, 0, v223, vcc
	v_cmp_gt_f32_e32 vcc, s47, v199
	v_sub_f32_e32 v152, v152, v202
	s_nop 0
	v_cndmask_b32_e64 v202, 0, 32, vcc
	v_ldexp_f32 v202, v199, v202
	v_log_f32_e32 v202, v202
	v_pk_add_f32 v[198:199], v[198:199], 1.0 op_sel_hi:[1,0] neg_lo:[1,0] neg_hi:[1,0]
	v_mul_f32_e32 v203, 0x3f317217, v202
	v_fma_f32 v203, v202, s96, -v203
	v_fmac_f32_e32 v203, 0x3377d1cf, v202
	v_fmac_f32_e32 v203, 0x3f317217, v202
	v_cmp_lt_f32_e64 s[14:15], |v202|, s1
	s_nop 1
	v_cndmask_b32_e64 v202, v202, v203, s[14:15]
	v_cndmask_b32_e32 v203, 0, v223, vcc
	v_sub_f32_e32 v202, v202, v203
	v_cmp_gt_f32_e32 vcc, s47, v132
	s_waitcnt lgkmcnt(0)
	s_nop 1
	v_add_f32_dpp v152, v152, v152 row_shr:1 row_mask:0xf bank_mask:0xf
	v_cndmask_b32_e64 v142, 0, 32, vcc
	v_ldexp_f32 v142, v132, v142
	v_log_f32_e32 v142, v142
	s_waitcnt lgkmcnt(0)
	s_nop 1
	v_add_f32_dpp v202, v202, v202 row_shr:1 row_mask:0xf bank_mask:0xf
	v_mul_f32_e32 v143, 0x3f317217, v142
	v_fma_f32 v143, v142, s96, -v143
	v_fmac_f32_e32 v143, 0x3377d1cf, v142
	v_fmac_f32_e32 v143, 0x3f317217, v142
	s_waitcnt lgkmcnt(0)
	s_nop 1
	v_add_f32_dpp v152, v152, v152 row_shr:2 row_mask:0xf bank_mask:0xf
	v_cmp_lt_f32_e64 s[14:15], |v142|, s1
	s_waitcnt lgkmcnt(0)
	s_nop 1
	v_add_f32_dpp v202, v202, v202 row_shr:2 row_mask:0xf bank_mask:0xf
	v_cndmask_b32_e64 v142, v142, v143, s[14:15]
	v_cndmask_b32_e32 v143, 0, v223, vcc
	v_cmp_gt_f32_e32 vcc, s47, v133
	v_sub_f32_e32 v142, v142, v143
	s_waitcnt lgkmcnt(0)
	s_nop 1
	v_add_f32_dpp v152, v152, v152 row_shr:4 row_mask:0xf bank_mask:0xf
	v_cndmask_b32_e64 v143, 0, 32, vcc
	v_ldexp_f32 v143, v133, v143
	v_log_f32_e32 v143, v143
	v_pk_add_f32 v[132:133], v[132:133], 1.0 op_sel_hi:[1,0] neg_lo:[1,0] neg_hi:[1,0]
	s_waitcnt lgkmcnt(0)
	s_nop 1
	v_add_f32_dpp v202, v202, v202 row_shr:4 row_mask:0xf bank_mask:0xf
	v_cmp_lt_f32_e64 s[14:15], |v143|, s1
	s_waitcnt lgkmcnt(0)
	s_nop 1
	v_add_f32_dpp v152, v152, v152 row_shr:8 row_mask:0xf bank_mask:0xf
	s_waitcnt lgkmcnt(0)
	s_nop 1
	v_add_f32_dpp v202, v202, v202 row_shr:8 row_mask:0xf bank_mask:0xf
	s_nop 1
	v_mov_b32_dpp v203, v152 row_newbcast:15 row_mask:0xf bank_mask:0xf
	s_nop 1
	v_mov_b32_dpp v204, v202 row_newbcast:15 row_mask:0xf bank_mask:0xf
	v_add_f32_e32 v152, v152, v201
	v_mul_f32_e32 v152, 0xbfb8aa3b, v152
	s_waitcnt lgkmcnt(1)
	v_add_f32_e32 v203, v201, v203
	v_add_f32_e32 v201, v202, v200
	s_waitcnt lgkmcnt(0)
	v_add_f32_e32 v202, v200, v204
	v_exp_f32_e32 v200, v152
	v_mul_f32_e32 v152, 0xbfb8aa3b, v201
	v_exp_f32_e32 v201, v152
	v_mul_f32_e32 v152, 0x3f317217, v143
	v_fma_f32 v152, v143, s96, -v152
	v_fmac_f32_e32 v152, 0x3377d1cf, v143
	v_fmac_f32_e32 v152, 0x3f317217, v143
	v_cndmask_b32_e64 v143, v143, v152, s[14:15]
	v_cndmask_b32_e32 v152, 0, v223, vcc
	v_sub_f32_e32 v143, v143, v152
	v_pk_mul_f32 v[198:199], v[198:199], v[200:201]
	s_waitcnt lgkmcnt(0)
	s_nop 1
	v_add_f32_dpp v142, v142, v142 row_shr:1 row_mask:0xf bank_mask:0xf
	s_waitcnt lgkmcnt(0)
	s_nop 1
	v_add_f32_dpp v143, v143, v143 row_shr:1 row_mask:0xf bank_mask:0xf
	s_waitcnt lgkmcnt(0)
	s_nop 1
	v_add_f32_dpp v142, v142, v142 row_shr:2 row_mask:0xf bank_mask:0xf
	s_waitcnt lgkmcnt(0)
	s_nop 1
	v_add_f32_dpp v143, v143, v143 row_shr:2 row_mask:0xf bank_mask:0xf
	s_waitcnt lgkmcnt(0)
	s_nop 1
	v_add_f32_dpp v142, v142, v142 row_shr:4 row_mask:0xf bank_mask:0xf
	s_waitcnt lgkmcnt(0)
	s_nop 1
	v_add_f32_dpp v143, v143, v143 row_shr:4 row_mask:0xf bank_mask:0xf
	s_waitcnt lgkmcnt(0)
	s_nop 1
	v_add_f32_dpp v142, v142, v142 row_shr:8 row_mask:0xf bank_mask:0xf
	v_add_f32_e32 v189, v142, v203
	s_waitcnt lgkmcnt(0)
	s_nop 1
	v_add_f32_dpp v143, v143, v143 row_shr:8 row_mask:0xf bank_mask:0xf
	s_nop 1
	v_mov_b32_dpp v152, v142 row_newbcast:15 row_mask:0xf bank_mask:0xf
	s_nop 1
	v_mov_b32_dpp v188, v143 row_newbcast:15 row_mask:0xf bank_mask:0xf
	s_waitcnt lgkmcnt(1)
	v_add_f32_e32 v142, v203, v152
	v_mul_f32_e32 v142, 0x3fb8aa3b, v142
	v_add_f32_e32 v152, v143, v202
	s_waitcnt lgkmcnt(0)
	v_add_f32_e32 v143, v202, v188
	v_exp_f32_e32 v142, v142
	v_mul_f32_e32 v143, 0x3fb8aa3b, v143
	v_exp_f32_e32 v143, v143
	v_mul_f32_e32 v152, 0xbfb8aa3b, v152
	v_mul_f32_e32 v188, v184, v142
	v_cvt_pk_bf16_f32 v188, v188, s0
	global_store_short v[182:183], v188, off
	v_mul_f32_e32 v188, v185, v143
	v_cvt_pk_bf16_f32 v188, v188, s0
	global_store_short v[182:183], v188, off offset:128
	v_mul_f32_e32 v188, v190, v142
	v_cvt_pk_bf16_f32 v188, v188, s0
	global_store_short v[182:183], v188, off offset:32
	v_mul_f32_e32 v188, v191, v143
	v_cvt_pk_bf16_f32 v188, v188, s0
	global_store_short v[182:183], v188, off offset:160
	v_mul_f32_e32 v188, v198, v142
	v_cvt_pk_bf16_f32 v188, v188, s0
	global_store_short v[182:183], v188, off offset:64
	v_mul_f32_e32 v188, v199, v143
	v_cvt_pk_bf16_f32 v188, v188, s0
	global_store_short v[182:183], v188, off offset:192
	v_mul_f32_e32 v188, 0xbfb8aa3b, v189
	v_exp_f32_e32 v188, v188
	v_exp_f32_e32 v189, v152
	s_nop 0
	v_pk_mul_f32 v[202:203], v[132:133], v[188:189]
	s_nop 0
	v_mul_f32_e32 v132, v142, v202
	v_cvt_pk_bf16_f32 v132, v132, s0
	global_store_short v[182:183], v132, off offset:96
	v_mul_f32_e32 v132, v143, v203
	v_cvt_pk_bf16_f32 v132, v132, s0
	global_store_short v[182:183], v132, off offset:224
	s_and_saveexec_b64 s[14:15], s[4:5]
	s_cbranch_execz .LBB0_1960
	s_add_u32 s28, s33, s90
	s_addc_u32 s29, s0, s91
	s_lshl_b64 s[88:89], s[86:87], 2
	s_add_u32 s88, s28, s88
	s_addc_u32 s89, s29, s89
	global_store_dwordx2 v237, v[142:143], s[88:89] offset:16
.LBB0_1960:
	s_or_b64 exec, exec, s[14:15]
	v_mul_f32_e32 v133, 0xbfb8aa3b, v56
	v_mul_f32_e32 v143, 0xbfb8aa3b, v57
	v_exp_f32_e32 v133, v133
	v_exp_f32_e32 v143, v143
	v_rcp_f32_e32 v132, v186
	v_rcp_f32_e32 v182, v196
	v_add_f32_e32 v133, 1.0, v133
	v_add_f32_e32 v143, 1.0, v143
	v_rcp_f32_e32 v142, v133
	v_rcp_f32_e32 v143, v143
	v_rcp_f32_e32 v133, v187
	v_rcp_f32_e32 v183, v197
	v_rcp_f32_e32 v186, v200
	v_pk_mul_f32 v[142:143], v[56:57], v[142:143]
	v_rcp_f32_e32 v187, v201
	v_pk_mul_f32 v[132:133], v[142:143], v[132:133]
	s_nop 0
	v_cvt_pk_bf16_f32 v142, v132, v133
	v_mul_f32_e32 v133, 0xbfb8aa3b, v40
	v_exp_f32_e32 v133, v133
	v_cvt_pk_bf16_f32 v132, v184, v185
	v_add_f32_e32 v133, 1.0, v133
	v_rcp_f32_e32 v184, v133
	v_mul_f32_e32 v133, 0xbfb8aa3b, v41
	v_exp_f32_e32 v133, v133
	s_nop 0
	v_add_f32_e32 v133, 1.0, v133
	v_rcp_f32_e32 v185, v133
	v_mul_f32_e32 v133, 0xbfb8aa3b, v24
	v_exp_f32_e32 v133, v133
	v_pk_mul_f32 v[184:185], v[40:41], v[184:185]
	s_nop 0
	v_pk_mul_f32 v[182:183], v[184:185], v[182:183]
	v_add_f32_e32 v133, 1.0, v133
	v_cvt_pk_bf16_f32 v184, v182, v183
	v_cvt_pk_bf16_f32 v182, v190, v191
	v_rcp_f32_e32 v190, v133
	v_mul_f32_e32 v133, 0xbfb8aa3b, v25
	v_exp_f32_e32 v133, v133
	s_nop 0
	v_add_f32_e32 v133, 1.0, v133
	v_rcp_f32_e32 v191, v133
	v_mul_f32_e32 v133, 0xbfb8aa3b, v8
	v_exp_f32_e32 v133, v133
	v_pk_mul_f32 v[190:191], v[24:25], v[190:191]
	s_nop 0
	v_pk_mul_f32 v[186:187], v[190:191], v[186:187]
	v_add_f32_e32 v133, 1.0, v133
	v_cvt_pk_bf16_f32 v196, v186, v187
	v_rcp_f32_e32 v186, v188
	v_rcp_f32_e32 v188, v133
	v_mul_f32_e32 v133, 0xbfb8aa3b, v9
	v_exp_f32_e32 v133, v133
	v_rcp_f32_e32 v187, v189
	v_cvt_pk_bf16_f32 v190, v198, v199
	v_mov_b32_e32 v199, s85
	v_add_f32_e32 v133, 1.0, v133
	v_rcp_f32_e32 v189, v133
	v_mul_f32_e32 v133, 0xbfb8aa3b, v50
	v_exp_f32_e32 v133, v133
	v_or_b32_e32 v198, s67, v162
	v_pk_mul_f32 v[188:189], v[8:9], v[188:189]
	v_lshlrev_b64 v[198:199], 7, v[198:199]
	v_pk_mul_f32 v[186:187], v[188:189], v[186:187]
	v_add_f32_e32 v133, 1.0, v133
	v_cvt_pk_bf16_f32 v188, v186, v187
	v_cvt_pk_bf16_f32 v186, v202, v203
	v_rcp_f32_e32 v202, v133
	v_mul_f32_e32 v133, 0xbfb8aa3b, v51
	v_exp_f32_e32 v133, v133
	v_lshl_add_u64 v[198:199], v[164:165], 0, v[198:199]
	v_add_f32_e32 v133, 1.0, v133
	v_rcp_f32_e32 v203, v133
	v_mul_f32_e32 v133, 0xbfb8aa3b, v34
	v_exp_f32_e32 v133, v133
	v_pk_fma_f32 v[202:203], v[202:203], v[130:131], v[128:129]
	s_nop 0
	v_cmp_gt_f32_e32 vcc, s47, v202
	v_add_f32_e32 v133, 1.0, v133
	v_rcp_f32_e32 v206, v133
	v_mul_f32_e32 v133, 0xbfb8aa3b, v35
	v_exp_f32_e32 v133, v133
	s_nop 0
	v_add_f32_e32 v133, 1.0, v133
	v_rcp_f32_e32 v207, v133
	v_mul_f32_e32 v133, 0xbfb8aa3b, v18
	v_exp_f32_e32 v133, v133
	v_pk_fma_f32 v[206:207], v[206:207], v[130:131], v[128:129]
	v_add_f32_e32 v133, 1.0, v133
	v_rcp_f32_e32 v204, v133
	v_mul_f32_e32 v133, 0xbfb8aa3b, v19
	v_exp_f32_e32 v133, v133
	s_nop 0
	v_add_f32_e32 v133, 1.0, v133
	v_rcp_f32_e32 v205, v133
	v_mul_f32_e32 v133, 0xbfb8aa3b, v2
	v_exp_f32_e32 v133, v133
	v_pk_fma_f32 v[204:205], v[204:205], v[130:131], v[128:129]
	v_add_f32_e32 v133, 1.0, v133
	v_rcp_f32_e32 v200, v133
	v_mul_f32_e32 v133, 0xbfb8aa3b, v3
	v_exp_f32_e32 v133, v133
	s_nop 0
	v_add_f32_e32 v133, 1.0, v133
	v_rcp_f32_e32 v201, v133
	v_cndmask_b32_e64 v133, 0, 32, vcc
	v_ldexp_f32 v133, v202, v133
	v_log_f32_e32 v133, v133
	v_pk_fma_f32 v[128:129], v[200:201], v[130:131], v[128:129]
	v_mul_f32_e32 v143, 0x3f317217, v133
	v_fma_f32 v143, v133, s96, -v143
	v_fmac_f32_e32 v143, 0x3377d1cf, v133
	v_fmac_f32_e32 v143, 0x3f317217, v133
	v_cmp_lt_f32_e64 s[14:15], |v133|, s1
	s_nop 1
	v_cndmask_b32_e64 v133, v133, v143, s[14:15]
	v_cndmask_b32_e32 v143, 0, v223, vcc
	v_cmp_gt_f32_e32 vcc, s47, v203
	v_sub_f32_e32 v133, v133, v143
	s_nop 0
	v_cndmask_b32_e64 v143, 0, 32, vcc
	v_ldexp_f32 v143, v203, v143
	v_log_f32_e32 v143, v143
	v_pk_add_f32 v[202:203], v[202:203], 1.0 op_sel_hi:[1,0] neg_lo:[1,0] neg_hi:[1,0]
	v_mul_f32_e32 v152, 0x3f317217, v143
	v_fma_f32 v152, v143, s96, -v152
	v_fmac_f32_e32 v152, 0x3377d1cf, v143
	v_fmac_f32_e32 v152, 0x3f317217, v143
	v_cmp_lt_f32_e64 s[14:15], |v143|, s1
	s_nop 1
	v_cndmask_b32_e64 v143, v143, v152, s[14:15]
	v_cndmask_b32_e32 v152, 0, v223, vcc
	v_cmp_gt_f32_e32 vcc, s47, v206
	v_sub_f32_e32 v143, v143, v152
	v_cndmask_b32_e64 v185, 0, 32, vcc
	v_ldexp_f32 v185, v206, v185
	v_log_f32_e32 v185, v185
	s_waitcnt lgkmcnt(0)
	s_nop 1
	v_add_f32_dpp v133, v133, v133 row_shr:1 row_mask:0xf bank_mask:0xf
	v_mul_f32_e32 v187, 0x3f317217, v185
	v_fma_f32 v187, v185, s96, -v187
	v_fmac_f32_e32 v187, 0x3377d1cf, v185
	v_fmac_f32_e32 v187, 0x3f317217, v185
	v_cmp_lt_f32_e64 s[14:15], |v185|, s1
	s_waitcnt lgkmcnt(0)
	v_cndmask_b32_e64 v185, v185, v187, s[14:15]
	v_cndmask_b32_e32 v187, 0, v223, vcc
	v_cmp_gt_f32_e32 vcc, s47, v207
	v_sub_f32_e32 v185, v185, v187
	s_nop 1
	v_add_f32_dpp v143, v143, v143 row_shr:1 row_mask:0xf bank_mask:0xf
	v_cndmask_b32_e64 v187, 0, 32, vcc
	v_ldexp_f32 v187, v207, v187
	v_log_f32_e32 v187, v187
	v_pk_add_f32 v[206:207], v[206:207], 1.0 op_sel_hi:[1,0] neg_lo:[1,0] neg_hi:[1,0]
	v_mul_f32_e32 v189, 0x3f317217, v187
	v_fma_f32 v189, v187, s96, -v189
	v_fmac_f32_e32 v189, 0x3377d1cf, v187
	v_fmac_f32_e32 v189, 0x3f317217, v187
	v_cmp_lt_f32_e64 s[14:15], |v187|, s1
	s_waitcnt lgkmcnt(0)
	s_nop 1
	v_add_f32_dpp v133, v133, v133 row_shr:2 row_mask:0xf bank_mask:0xf
	v_cndmask_b32_e64 v187, v187, v189, s[14:15]
	v_cndmask_b32_e32 v189, 0, v223, vcc
	v_sub_f32_e32 v187, v187, v189
	v_cmp_gt_f32_e32 vcc, s47, v204
	s_waitcnt lgkmcnt(1)
	s_nop 1
	v_add_f32_dpp v185, v185, v185 row_shr:1 row_mask:0xf bank_mask:0xf
	s_waitcnt lgkmcnt(1)
	s_nop 1
	v_add_f32_dpp v143, v143, v143 row_shr:2 row_mask:0xf bank_mask:0xf
	s_waitcnt lgkmcnt(1)
	s_nop 1
	v_add_f32_dpp v187, v187, v187 row_shr:1 row_mask:0xf bank_mask:0xf
	s_waitcnt lgkmcnt(1)
	s_nop 1
	v_add_f32_dpp v133, v133, v133 row_shr:4 row_mask:0xf bank_mask:0xf
	s_waitcnt lgkmcnt(1)
	s_nop 1
	v_add_f32_dpp v185, v185, v185 row_shr:2 row_mask:0xf bank_mask:0xf
	s_waitcnt lgkmcnt(1)
	s_nop 1
	v_add_f32_dpp v143, v143, v143 row_shr:4 row_mask:0xf bank_mask:0xf
	s_waitcnt lgkmcnt(1)
	s_nop 1
	v_add_f32_dpp v187, v187, v187 row_shr:2 row_mask:0xf bank_mask:0xf
	s_waitcnt lgkmcnt(1)
	s_nop 1
	v_add_f32_dpp v133, v133, v133 row_shr:8 row_mask:0xf bank_mask:0xf
	s_waitcnt lgkmcnt(1)
	s_nop 1
	v_add_f32_dpp v185, v185, v185 row_shr:4 row_mask:0xf bank_mask:0xf
	s_waitcnt lgkmcnt(1)
	s_nop 1
	v_add_f32_dpp v143, v143, v143 row_shr:8 row_mask:0xf bank_mask:0xf
	s_nop 1
	v_mov_b32_dpp v152, v133 row_newbcast:15 row_mask:0xf bank_mask:0xf
	v_add_f32_e32 v133, 0, v133
	s_nop 1
	v_mov_b32_dpp v183, v143 row_newbcast:15 row_mask:0xf bank_mask:0xf
	v_add_f32_e32 v143, 0, v143
	v_mul_f32_e32 v133, 0xbfb8aa3b, v133
	s_waitcnt lgkmcnt(2)
	v_exp_f32_e32 v208, v133
	v_mul_f32_e32 v133, 0xbfb8aa3b, v143
	s_nop 1
	v_add_f32_dpp v187, v187, v187 row_shr:4 row_mask:0xf bank_mask:0xf
	v_exp_f32_e32 v209, v133
	v_mul_f32_e32 v133, 0xbfb8aa3b, v58
	v_exp_f32_e32 v133, v133
	s_waitcnt lgkmcnt(2)
	v_add_f32_e32 v152, 0, v152
	s_waitcnt lgkmcnt(0)
	s_nop 1
	v_add_f32_dpp v185, v185, v185 row_shr:8 row_mask:0xf bank_mask:0xf
	v_add_f32_e32 v133, 1.0, v133
	v_rcp_f32_e32 v210, v133
	v_mul_f32_e32 v133, 0xbfb8aa3b, v59
	v_exp_f32_e32 v133, v133
	v_pk_mul_f32 v[202:203], v[202:203], v[208:209]
	s_waitcnt lgkmcnt(0)
	s_nop 1
	v_add_f32_dpp v187, v187, v187 row_shr:8 row_mask:0xf bank_mask:0xf
	v_add_f32_e32 v133, 1.0, v133
	v_rcp_f32_e32 v211, v133
	s_nop 1
	v_mov_b32_dpp v189, v185 row_newbcast:15 row_mask:0xf bank_mask:0xf
	s_nop 1
	v_mov_b32_dpp v191, v187 row_newbcast:15 row_mask:0xf bank_mask:0xf
	v_rcp_f32_e32 v208, v208
	v_rcp_f32_e32 v209, v209
	v_add_f32_e32 v183, 0, v183
	v_pk_mul_f32 v[210:211], v[58:59], v[210:211]
	v_add_f32_e32 v185, v185, v152
	v_pk_mul_f32 v[208:209], v[210:211], v[208:209]
	s_waitcnt lgkmcnt(1)
	v_add_f32_e32 v152, v152, v189
	v_add_f32_e32 v187, v187, v183
	s_waitcnt lgkmcnt(0)
	v_add_f32_e32 v189, v183, v191
	v_mul_f32_e32 v183, 0xbfb8aa3b, v185
	v_cvt_pk_bf16_f32 v143, v208, v209
	v_exp_f32_e32 v208, v183
	v_mul_f32_e32 v183, 0xbfb8aa3b, v187
	v_cndmask_b32_e64 v187, 0, 32, vcc
	v_ldexp_f32 v187, v204, v187
	v_log_f32_e32 v187, v187
	v_exp_f32_e32 v209, v183
	v_mul_f32_e32 v183, 0xbfb8aa3b, v42
	v_exp_f32_e32 v183, v183
	v_mul_f32_e32 v191, 0x3f317217, v187
	v_fma_f32 v191, v187, s96, -v191
	v_fmac_f32_e32 v191, 0x3377d1cf, v187
	v_fmac_f32_e32 v191, 0x3f317217, v187
	v_cmp_lt_f32_e64 s[14:15], |v187|, s1
	v_add_f32_e32 v183, 1.0, v183
	v_rcp_f32_e32 v210, v183
	v_cndmask_b32_e64 v187, v187, v191, s[14:15]
	v_cndmask_b32_e32 v191, 0, v223, vcc
	v_cmp_gt_f32_e32 vcc, s47, v205
	v_sub_f32_e32 v187, v187, v191
	v_mul_f32_e32 v183, 0xbfb8aa3b, v43
	v_cndmask_b32_e64 v191, 0, 32, vcc
	v_ldexp_f32 v191, v205, v191
	v_log_f32_e32 v191, v191
	v_exp_f32_e32 v183, v183
	v_pk_mul_f32 v[206:207], v[206:207], v[208:209]
	v_rcp_f32_e32 v208, v208
	v_mul_f32_e32 v197, 0x3f317217, v191
	v_fma_f32 v197, v191, s96, -v197
	v_fmac_f32_e32 v197, 0x3377d1cf, v191
	v_fmac_f32_e32 v197, 0x3f317217, v191
	v_cmp_lt_f32_e64 s[14:15], |v191|, s1
	v_add_f32_e32 v183, 1.0, v183
	v_rcp_f32_e32 v211, v183
	v_cndmask_b32_e64 v191, v191, v197, s[14:15]
	v_cndmask_b32_e32 v197, 0, v223, vcc
	v_sub_f32_e32 v191, v191, v197
	v_rcp_f32_e32 v209, v209
	v_pk_mul_f32 v[210:211], v[42:43], v[210:211]
	v_cmp_gt_f32_e32 vcc, s47, v128
	v_cvt_pk_bf16_f32 v133, v202, v203
	s_waitcnt lgkmcnt(0)
	s_nop 1
	v_add_f32_dpp v187, v187, v187 row_shr:1 row_mask:0xf bank_mask:0xf
	v_pk_mul_f32 v[208:209], v[210:211], v[208:209]
	v_cndmask_b32_e64 v130, 0, 32, vcc
	v_cvt_pk_bf16_f32 v185, v208, v209
	v_ldexp_f32 v130, v128, v130
	s_waitcnt lgkmcnt(0)
	s_nop 1
	v_add_f32_dpp v191, v191, v191 row_shr:1 row_mask:0xf bank_mask:0xf
	v_log_f32_e32 v130, v130
	v_pk_add_f32 v[204:205], v[204:205], 1.0 op_sel_hi:[1,0] neg_lo:[1,0] neg_hi:[1,0]
	v_cvt_pk_bf16_f32 v183, v206, v207
	s_waitcnt lgkmcnt(0)
	s_nop 1
	v_add_f32_dpp v187, v187, v187 row_shr:2 row_mask:0xf bank_mask:0xf
	v_mul_f32_e32 v131, 0x3f317217, v130
	v_fma_f32 v131, v130, s96, -v131
	v_fmac_f32_e32 v131, 0x3377d1cf, v130
	v_fmac_f32_e32 v131, 0x3f317217, v130
	s_waitcnt lgkmcnt(0)
	s_nop 1
	v_add_f32_dpp v191, v191, v191 row_shr:2 row_mask:0xf bank_mask:0xf
	v_cmp_lt_f32_e64 s[14:15], |v130|, s1
	s_waitcnt lgkmcnt(0)
	s_nop 1
	v_add_f32_dpp v187, v187, v187 row_shr:4 row_mask:0xf bank_mask:0xf
	v_cndmask_b32_e64 v130, v130, v131, s[14:15]
	v_cndmask_b32_e32 v131, 0, v223, vcc
	v_cmp_gt_f32_e32 vcc, s47, v129
	v_sub_f32_e32 v130, v130, v131
	s_waitcnt lgkmcnt(0)
	s_nop 1
	v_add_f32_dpp v191, v191, v191 row_shr:4 row_mask:0xf bank_mask:0xf
	v_cndmask_b32_e64 v131, 0, 32, vcc
	v_ldexp_f32 v131, v129, v131
	v_log_f32_e32 v131, v131
	v_pk_add_f32 v[128:129], v[128:129], 1.0 op_sel_hi:[1,0] neg_lo:[1,0] neg_hi:[1,0]
	s_waitcnt lgkmcnt(0)
	s_nop 1
	v_add_f32_dpp v187, v187, v187 row_shr:8 row_mask:0xf bank_mask:0xf
	v_cmp_lt_f32_e64 s[14:15], |v131|, s1
	s_waitcnt lgkmcnt(0)
	s_nop 1
	v_add_f32_dpp v191, v191, v191 row_shr:8 row_mask:0xf bank_mask:0xf
	s_nop 1
	v_mov_b32_dpp v208, v191 row_newbcast:15 row_mask:0xf bank_mask:0xf
	s_nop 1
	v_mov_b32_dpp v197, v187 row_newbcast:15 row_mask:0xf bank_mask:0xf
	v_add_f32_e32 v187, v187, v152
	v_add_f32_e32 v191, v191, v189
	v_mul_f32_e32 v187, 0xbfb8aa3b, v187
	s_waitcnt lgkmcnt(1)
	v_add_f32_e32 v189, v189, v208
	v_exp_f32_e32 v208, v187
	v_mul_f32_e32 v187, 0xbfb8aa3b, v191
	v_exp_f32_e32 v209, v187
	v_mul_f32_e32 v187, 0xbfb8aa3b, v26
	v_exp_f32_e32 v187, v187
	s_waitcnt lgkmcnt(0)
	v_add_f32_e32 v152, v152, v197
	v_pk_mul_f32 v[204:205], v[204:205], v[208:209]
	v_rcp_f32_e32 v208, v208
	v_add_f32_e32 v187, 1.0, v187
	v_rcp_f32_e32 v210, v187
	v_mul_f32_e32 v187, 0xbfb8aa3b, v27
	v_exp_f32_e32 v187, v187
	v_rcp_f32_e32 v209, v209
	v_cvt_pk_bf16_f32 v191, v204, v205
	v_add_f32_e32 v187, 1.0, v187
	v_rcp_f32_e32 v211, v187
	v_mul_f32_e32 v187, 0x3f317217, v131
	v_fma_f32 v187, v131, s96, -v187
	v_fmac_f32_e32 v187, 0x3377d1cf, v131
	v_fmac_f32_e32 v187, 0x3f317217, v131
	v_cndmask_b32_e64 v131, v131, v187, s[14:15]
	v_cndmask_b32_e32 v187, 0, v223, vcc
	v_sub_f32_e32 v131, v131, v187
	v_pk_mul_f32 v[210:211], v[26:27], v[210:211]
	s_waitcnt lgkmcnt(0)
	s_nop 1
	v_add_f32_dpp v130, v130, v130 row_shr:1 row_mask:0xf bank_mask:0xf
	v_pk_mul_f32 v[208:209], v[210:211], v[208:209]
	s_waitcnt lgkmcnt(0)
	s_nop 1
	v_add_f32_dpp v131, v131, v131 row_shr:1 row_mask:0xf bank_mask:0xf
	v_cvt_pk_bf16_f32 v197, v208, v209
	s_waitcnt lgkmcnt(0)
	s_nop 1
	v_add_f32_dpp v130, v130, v130 row_shr:2 row_mask:0xf bank_mask:0xf
	s_waitcnt lgkmcnt(0)
	s_nop 1
	v_add_f32_dpp v131, v131, v131 row_shr:2 row_mask:0xf bank_mask:0xf
	s_waitcnt lgkmcnt(0)
	s_nop 1
	v_add_f32_dpp v130, v130, v130 row_shr:4 row_mask:0xf bank_mask:0xf
	s_waitcnt lgkmcnt(0)
	s_nop 1
	v_add_f32_dpp v131, v131, v131 row_shr:4 row_mask:0xf bank_mask:0xf
	s_waitcnt lgkmcnt(0)
	s_nop 1
	v_add_f32_dpp v130, v130, v130 row_shr:8 row_mask:0xf bank_mask:0xf
	v_add_f32_e32 v201, v130, v152
	s_waitcnt lgkmcnt(0)
	s_nop 1
	v_add_f32_dpp v131, v131, v131 row_shr:8 row_mask:0xf bank_mask:0xf
	s_nop 1
	v_mov_b32_dpp v187, v130 row_newbcast:15 row_mask:0xf bank_mask:0xf
	s_nop 1
	v_mov_b32_dpp v200, v131 row_newbcast:15 row_mask:0xf bank_mask:0xf
	s_waitcnt lgkmcnt(1)
	v_add_f32_e32 v130, v152, v187
	v_mul_f32_e32 v130, 0x3fb8aa3b, v130
	v_add_f32_e32 v152, v131, v189
	s_waitcnt lgkmcnt(0)
	v_add_f32_e32 v131, v189, v200
	v_exp_f32_e32 v130, v130
	v_mul_f32_e32 v131, 0x3fb8aa3b, v131
	v_exp_f32_e32 v131, v131
	v_mul_f32_e32 v187, v202, v130
	v_cvt_pk_bf16_f32 v187, v187, s0
	global_store_short v[198:199], v187, off
	v_mul_f32_e32 v187, v203, v131
	v_cvt_pk_bf16_f32 v187, v187, s0
	global_store_short v[198:199], v187, off offset:128
	global_store_dwordx2 v[134:135], v[142:143], off offset:8
	global_store_dwordx2 v[140:141], v[132:133], off offset:8
	v_mul_f32_e32 v132, v206, v130
	v_cvt_pk_bf16_f32 v132, v132, s0
	global_store_short v[198:199], v132, off offset:32
	v_mul_f32_e32 v132, v207, v131
	v_cvt_pk_bf16_f32 v132, v132, s0
	global_store_short v[198:199], v132, off offset:160
	global_store_dwordx2 v[174:175], v[184:185], off offset:8
	global_store_dwordx2 v[176:177], v[182:183], off offset:8
	v_mul_f32_e32 v132, v204, v130
	v_cvt_pk_bf16_f32 v132, v132, s0
	global_store_short v[198:199], v132, off offset:64
	v_mul_f32_e32 v132, v205, v131
	v_cvt_pk_bf16_f32 v132, v132, s0
	global_store_short v[198:199], v132, off offset:192
	global_store_dwordx2 v[178:179], v[196:197], off offset:8
	global_store_dwordx2 v[180:181], v[190:191], off offset:8
	v_mul_f32_e32 v132, 0xbfb8aa3b, v201
	v_mul_f32_e32 v133, 0xbfb8aa3b, v152
	v_exp_f32_e32 v132, v132
	v_exp_f32_e32 v133, v133
	v_mul_f32_e32 v135, 0xbfb8aa3b, v11
	v_exp_f32_e32 v135, v135
	v_pk_mul_f32 v[128:129], v[128:129], v[132:133]
	s_nop 0
	v_mul_f32_e32 v134, v130, v128
	v_cvt_pk_bf16_f32 v134, v134, s0
	global_store_short v[198:199], v134, off offset:96
	v_mul_f32_e32 v134, v131, v129
	v_cvt_pk_bf16_f32 v134, v134, s0
	global_store_short v[198:199], v134, off offset:224
	v_mul_f32_e32 v134, 0xbfb8aa3b, v10
	v_exp_f32_e32 v134, v134
	v_add_f32_e32 v135, 1.0, v135
	v_rcp_f32_e32 v135, v135
	v_rcp_f32_e32 v132, v132
	v_add_f32_e32 v134, 1.0, v134
	v_rcp_f32_e32 v134, v134
	v_rcp_f32_e32 v133, v133
	v_cvt_pk_bf16_f32 v187, v128, v129
	v_pk_mul_f32 v[134:135], v[10:11], v[134:135]
	s_nop 0
	v_pk_mul_f32 v[132:133], v[134:135], v[132:133]
	s_nop 0
	v_cvt_pk_bf16_f32 v189, v132, v133
	global_store_dwordx2 v[136:137], v[188:189], off offset:8
	global_store_dwordx2 v[138:139], v[186:187], off offset:8
	s_and_saveexec_b64 s[14:15], s[4:5]
	s_cbranch_execz .LBB0_1962
	s_add_u32 s28, s33, s90
	s_addc_u32 s29, s0, s91
	s_lshl_b64 s[86:87], s[86:87], 2
	s_add_u32 s86, s28, s86
	s_addc_u32 s87, s29, s87
	global_store_dwordx2 v237, v[130:131], s[86:87] offset:24
